# adds hand-scheduled branch-merge epilogues (P5) and the beta/log-decay pass on f32 matrix cores (v_mfma_f32_16x16x4_f32, 16 rows per wave) to the hand-scheduled GEMM epilogues and sample-row blocks
# speedup vs baseline: 1.0415x; 1.0040x over previous
.LBB0_435:
	s_or_b64 exec, exec, s[10:11]
	s_ashr_i32 s10, s35, 6
	s_waitcnt lgkmcnt(0)
	s_add_i32 s12, s10, s33
	s_cmp_lt_i32 s12, 0x10100
	s_barrier
	v_and_b32_e32 v0, 63, v206
	v_lshrrev_b32_e32 v5, 6, v206
	s_load_dwordx2 s[88:89], s[0:1], 0x88
	s_load_dwordx2 s[92:93], s[0:1], 0x90
	v_readfirstlane_b32 s86, v5
	v_and_b32_e32 v1, 15, v0
	v_lshrrev_b32_e32 v2, 4, v0
	s_add_u32 s87, s33, s86
	v_lshlrev_b32_e32 v3, 11, v1
	v_lshl_add_u32 v3, v2, 4, v3
	v_and_b32_e32 v4, 7, v0
	v_lshlrev_b32_e32 v4, 12, v4
	v_lshl_add_u32 v4, v2, 5, v4
	v_and_b32_e32 v5, 3, v0
	v_lshlrev_b32_e32 v5, 2, v5
	v_xor_b32_e32 v8, 1, v0
	v_lshlrev_b32_e32 v8, 2, v8
	v_xor_b32_e32 v9, 2, v0
	v_lshlrev_b32_e32 v9, 2, v9
	v_xor_b32_e32 v10, 4, v0
	v_lshlrev_b32_e32 v10, 2, v10
	v_xor_b32_e32 v11, 8, v0
	v_lshlrev_b32_e32 v11, 2, v11
	v_lshlrev_b32_e32 v12, 8, v2
	v_lshl_add_u32 v12, v1, 2, v12
	v_lshlrev_b32_e32 v13, 7, v2
	v_lshl_add_u32 v13, v1, 2, v13
	v_cmp_lt_u32_e64 s[98:99], v1, 4
	v_cmp_lt_u32_e64 s[100:101], v1, 8
	s_waitcnt lgkmcnt(0)
	global_load_dword v7, v5, s[88:89]
	global_load_dword v6, v5, s[92:93]
	s_waitcnt vmcnt(0)
	v_mul_f32_e32 v7, 0x3fb8aa3b, v7
	v_exp_f32_e32 v7, v7
	s_nop 1
.Lbd_loop:
	s_cmp_ge_u32 s87, 0x1010
	s_cbranch_scc1 .Lbd_done
	s_lshl_b32 s32, s87, 15
	s_add_u32 s88, s96, s32
	s_addc_u32 s89, s97, 0
	s_add_u32 s88, s88, 0x9e00000
	s_addc_u32 s89, s89, 0
	s_lshl_b32 s32, s87, 10
	s_add_u32 s92, s96, s32
	s_addc_u32 s93, s97, 0
	s_add_u32 s92, s92, 0x4600000
	s_addc_u32 s93, s93, 0
	s_lshl_b32 s32, s87, 9
	s_add_u32 s94, s96, s32
	s_addc_u32 s95, s97, 0
	s_add_u32 s94, s94, 0x5b00000
	s_addc_u32 s95, s95, 0
	global_load_dword v56, v12, s[92:93]
	global_load_dword v57, v12, s[92:93] offset:64
	global_load_dword v58, v12, s[92:93] offset:128
	global_load_dword v59, v12, s[92:93] offset:192
	global_load_dwordx4 v[64:67], v3, s[88:89]
	global_load_dwordx4 v[68:71], v3, s[88:89] offset:64
	global_load_dwordx4 v[72:75], v3, s[88:89] offset:128
	global_load_dwordx4 v[76:79], v3, s[88:89] offset:192
	global_load_dwordx4 v[80:83], v3, s[88:89] offset:256
	global_load_dwordx4 v[84:87], v3, s[88:89] offset:320
	global_load_dwordx4 v[88:91], v3, s[88:89] offset:384
	global_load_dwordx4 v[92:95], v3, s[88:89] offset:448
	global_load_dwordx4 v[96:99], v3, s[88:89] offset:512
	global_load_dwordx4 v[100:103], v3, s[88:89] offset:576
	global_load_dwordx4 v[104:107], v3, s[88:89] offset:640
	global_load_dwordx4 v[108:111], v3, s[88:89] offset:704
	global_load_dwordx4 v[112:115], v3, s[88:89] offset:768
	global_load_dwordx4 v[116:119], v3, s[88:89] offset:832
	global_load_dwordx4 v[120:123], v3, s[88:89] offset:896
	global_load_dwordx4 v[124:127], v3, s[88:89] offset:960
	global_load_dwordx4 v[128:131], v3, s[88:89] offset:1024
	global_load_dwordx4 v[132:135], v3, s[88:89] offset:1088
	global_load_dwordx4 v[136:139], v3, s[88:89] offset:1152
	global_load_dwordx4 v[140:143], v3, s[88:89] offset:1216
	global_load_dwordx4 v[144:147], v3, s[88:89] offset:1280
	global_load_dwordx4 v[148:151], v3, s[88:89] offset:1344
	global_load_dwordx4 v[152:155], v3, s[88:89] offset:1408
	global_load_dwordx4 v[156:159], v3, s[88:89] offset:1472
	global_load_dwordx4 v[160:163], v3, s[88:89] offset:1536
	global_load_dwordx4 v[164:167], v3, s[88:89] offset:1600
	global_load_dwordx4 v[168:171], v3, s[88:89] offset:1664
	global_load_dwordx4 v[172:175], v3, s[88:89] offset:1728
	global_load_dwordx4 v[176:179], v3, s[88:89] offset:1792
	global_load_dwordx4 v[180:183], v3, s[88:89] offset:1856
	global_load_dwordx4 v[184:187], v3, s[88:89] offset:1920
	global_load_dwordx4 v[188:191], v3, s[88:89] offset:1984
	v_mov_b32_e32 v16, 0
	v_mov_b32_e32 v20, 0
	v_mov_b32_e32 v17, 0
	v_mov_b32_e32 v21, 0
	v_mov_b32_e32 v18, 0
	v_mov_b32_e32 v22, 0
	v_mov_b32_e32 v19, 0
	v_mov_b32_e32 v23, 0
	ds_read_b128 v[24:27], v4
	ds_read_b128 v[28:31], v4 offset:16
	ds_read_b128 v[32:35], v4 offset:128
	ds_read_b128 v[36:39], v4 offset:144
	s_waitcnt vmcnt(31)
	v_lshlrev_b32_e32 v40, 16, v64
	v_and_b32_e32 v41, 0xffff0000, v64
	v_lshlrev_b32_e32 v42, 16, v65
	v_and_b32_e32 v43, 0xffff0000, v65
	v_lshlrev_b32_e32 v44, 16, v66
	v_and_b32_e32 v45, 0xffff0000, v66
	v_lshlrev_b32_e32 v46, 16, v67
	v_and_b32_e32 v47, 0xffff0000, v67
	s_waitcnt lgkmcnt(2)
	v_mfma_f32_16x16x4_f32 v[16:19], v40, v24, v[16:19]
	v_mfma_f32_16x16x4_f32 v[20:23], v41, v25, v[20:23]
	v_mfma_f32_16x16x4_f32 v[16:19], v42, v26, v[16:19]
	v_mfma_f32_16x16x4_f32 v[20:23], v43, v27, v[20:23]
	v_mfma_f32_16x16x4_f32 v[16:19], v44, v28, v[16:19]
	v_mfma_f32_16x16x4_f32 v[20:23], v45, v29, v[20:23]
	v_mfma_f32_16x16x4_f32 v[16:19], v46, v30, v[16:19]
	v_mfma_f32_16x16x4_f32 v[20:23], v47, v31, v[20:23]
	ds_read_b128 v[24:27], v4 offset:256
	ds_read_b128 v[28:31], v4 offset:272
	s_waitcnt vmcnt(30)
	v_lshlrev_b32_e32 v48, 16, v68
	v_and_b32_e32 v49, 0xffff0000, v68
	v_lshlrev_b32_e32 v50, 16, v69
	v_and_b32_e32 v51, 0xffff0000, v69
	v_lshlrev_b32_e32 v52, 16, v70
	v_and_b32_e32 v53, 0xffff0000, v70
	v_lshlrev_b32_e32 v54, 16, v71
	v_and_b32_e32 v55, 0xffff0000, v71
	s_waitcnt lgkmcnt(2)
	v_mfma_f32_16x16x4_f32 v[16:19], v48, v32, v[16:19]
	v_mfma_f32_16x16x4_f32 v[20:23], v49, v33, v[20:23]
	v_mfma_f32_16x16x4_f32 v[16:19], v50, v34, v[16:19]
	v_mfma_f32_16x16x4_f32 v[20:23], v51, v35, v[20:23]
	v_mfma_f32_16x16x4_f32 v[16:19], v52, v36, v[16:19]
	v_mfma_f32_16x16x4_f32 v[20:23], v53, v37, v[20:23]
	v_mfma_f32_16x16x4_f32 v[16:19], v54, v38, v[16:19]
	v_mfma_f32_16x16x4_f32 v[20:23], v55, v39, v[20:23]
	ds_read_b128 v[32:35], v4 offset:384
	ds_read_b128 v[36:39], v4 offset:400
	s_waitcnt vmcnt(29)
	v_lshlrev_b32_e32 v40, 16, v72
	v_and_b32_e32 v41, 0xffff0000, v72
	v_lshlrev_b32_e32 v42, 16, v73
	v_and_b32_e32 v43, 0xffff0000, v73
	v_lshlrev_b32_e32 v44, 16, v74
	v_and_b32_e32 v45, 0xffff0000, v74
	v_lshlrev_b32_e32 v46, 16, v75
	v_and_b32_e32 v47, 0xffff0000, v75
	s_waitcnt lgkmcnt(2)
	v_mfma_f32_16x16x4_f32 v[16:19], v40, v24, v[16:19]
	v_mfma_f32_16x16x4_f32 v[20:23], v41, v25, v[20:23]
	v_mfma_f32_16x16x4_f32 v[16:19], v42, v26, v[16:19]
	v_mfma_f32_16x16x4_f32 v[20:23], v43, v27, v[20:23]
	v_mfma_f32_16x16x4_f32 v[16:19], v44, v28, v[16:19]
	v_mfma_f32_16x16x4_f32 v[20:23], v45, v29, v[20:23]
	v_mfma_f32_16x16x4_f32 v[16:19], v46, v30, v[16:19]
	v_mfma_f32_16x16x4_f32 v[20:23], v47, v31, v[20:23]
	ds_read_b128 v[24:27], v4 offset:512
	ds_read_b128 v[28:31], v4 offset:528
	s_waitcnt vmcnt(28)
	v_lshlrev_b32_e32 v48, 16, v76
	v_and_b32_e32 v49, 0xffff0000, v76
	v_lshlrev_b32_e32 v50, 16, v77
	v_and_b32_e32 v51, 0xffff0000, v77
	v_lshlrev_b32_e32 v52, 16, v78
	v_and_b32_e32 v53, 0xffff0000, v78
	v_lshlrev_b32_e32 v54, 16, v79
	v_and_b32_e32 v55, 0xffff0000, v79
	s_waitcnt lgkmcnt(2)
	v_mfma_f32_16x16x4_f32 v[16:19], v48, v32, v[16:19]
	v_mfma_f32_16x16x4_f32 v[20:23], v49, v33, v[20:23]
	v_mfma_f32_16x16x4_f32 v[16:19], v50, v34, v[16:19]
	v_mfma_f32_16x16x4_f32 v[20:23], v51, v35, v[20:23]
	v_mfma_f32_16x16x4_f32 v[16:19], v52, v36, v[16:19]
	v_mfma_f32_16x16x4_f32 v[20:23], v53, v37, v[20:23]
	v_mfma_f32_16x16x4_f32 v[16:19], v54, v38, v[16:19]
	v_mfma_f32_16x16x4_f32 v[20:23], v55, v39, v[20:23]
	ds_read_b128 v[32:35], v4 offset:640
	ds_read_b128 v[36:39], v4 offset:656
	s_waitcnt vmcnt(27)
	v_lshlrev_b32_e32 v40, 16, v80
	v_and_b32_e32 v41, 0xffff0000, v80
	v_lshlrev_b32_e32 v42, 16, v81
	v_and_b32_e32 v43, 0xffff0000, v81
	v_lshlrev_b32_e32 v44, 16, v82
	v_and_b32_e32 v45, 0xffff0000, v82
	v_lshlrev_b32_e32 v46, 16, v83
	v_and_b32_e32 v47, 0xffff0000, v83
	s_waitcnt lgkmcnt(2)
	v_mfma_f32_16x16x4_f32 v[16:19], v40, v24, v[16:19]
	v_mfma_f32_16x16x4_f32 v[20:23], v41, v25, v[20:23]
	v_mfma_f32_16x16x4_f32 v[16:19], v42, v26, v[16:19]
	v_mfma_f32_16x16x4_f32 v[20:23], v43, v27, v[20:23]
	v_mfma_f32_16x16x4_f32 v[16:19], v44, v28, v[16:19]
	v_mfma_f32_16x16x4_f32 v[20:23], v45, v29, v[20:23]
	v_mfma_f32_16x16x4_f32 v[16:19], v46, v30, v[16:19]
	v_mfma_f32_16x16x4_f32 v[20:23], v47, v31, v[20:23]
	ds_read_b128 v[24:27], v4 offset:768
	ds_read_b128 v[28:31], v4 offset:784
	s_waitcnt vmcnt(26)
	v_lshlrev_b32_e32 v48, 16, v84
	v_and_b32_e32 v49, 0xffff0000, v84
	v_lshlrev_b32_e32 v50, 16, v85
	v_and_b32_e32 v51, 0xffff0000, v85
	v_lshlrev_b32_e32 v52, 16, v86
	v_and_b32_e32 v53, 0xffff0000, v86
	v_lshlrev_b32_e32 v54, 16, v87
	v_and_b32_e32 v55, 0xffff0000, v87
	s_waitcnt lgkmcnt(2)
	v_mfma_f32_16x16x4_f32 v[16:19], v48, v32, v[16:19]
	v_mfma_f32_16x16x4_f32 v[20:23], v49, v33, v[20:23]
	v_mfma_f32_16x16x4_f32 v[16:19], v50, v34, v[16:19]
	v_mfma_f32_16x16x4_f32 v[20:23], v51, v35, v[20:23]
	v_mfma_f32_16x16x4_f32 v[16:19], v52, v36, v[16:19]
	v_mfma_f32_16x16x4_f32 v[20:23], v53, v37, v[20:23]
	v_mfma_f32_16x16x4_f32 v[16:19], v54, v38, v[16:19]
	v_mfma_f32_16x16x4_f32 v[20:23], v55, v39, v[20:23]
	ds_read_b128 v[32:35], v4 offset:896
	ds_read_b128 v[36:39], v4 offset:912
	s_waitcnt vmcnt(25)
	v_lshlrev_b32_e32 v40, 16, v88
	v_and_b32_e32 v41, 0xffff0000, v88
	v_lshlrev_b32_e32 v42, 16, v89
	v_and_b32_e32 v43, 0xffff0000, v89
	v_lshlrev_b32_e32 v44, 16, v90
	v_and_b32_e32 v45, 0xffff0000, v90
	v_lshlrev_b32_e32 v46, 16, v91
	v_and_b32_e32 v47, 0xffff0000, v91
	s_waitcnt lgkmcnt(2)
	v_mfma_f32_16x16x4_f32 v[16:19], v40, v24, v[16:19]
	v_mfma_f32_16x16x4_f32 v[20:23], v41, v25, v[20:23]
	v_mfma_f32_16x16x4_f32 v[16:19], v42, v26, v[16:19]
	v_mfma_f32_16x16x4_f32 v[20:23], v43, v27, v[20:23]
	v_mfma_f32_16x16x4_f32 v[16:19], v44, v28, v[16:19]
	v_mfma_f32_16x16x4_f32 v[20:23], v45, v29, v[20:23]
	v_mfma_f32_16x16x4_f32 v[16:19], v46, v30, v[16:19]
	v_mfma_f32_16x16x4_f32 v[20:23], v47, v31, v[20:23]
	ds_read_b128 v[24:27], v4 offset:1024
	ds_read_b128 v[28:31], v4 offset:1040
	s_waitcnt vmcnt(24)
	v_lshlrev_b32_e32 v48, 16, v92
	v_and_b32_e32 v49, 0xffff0000, v92
	v_lshlrev_b32_e32 v50, 16, v93
	v_and_b32_e32 v51, 0xffff0000, v93
	v_lshlrev_b32_e32 v52, 16, v94
	v_and_b32_e32 v53, 0xffff0000, v94
	v_lshlrev_b32_e32 v54, 16, v95
	v_and_b32_e32 v55, 0xffff0000, v95
	s_waitcnt lgkmcnt(2)
	v_mfma_f32_16x16x4_f32 v[16:19], v48, v32, v[16:19]
	v_mfma_f32_16x16x4_f32 v[20:23], v49, v33, v[20:23]
	v_mfma_f32_16x16x4_f32 v[16:19], v50, v34, v[16:19]
	v_mfma_f32_16x16x4_f32 v[20:23], v51, v35, v[20:23]
	v_mfma_f32_16x16x4_f32 v[16:19], v52, v36, v[16:19]
	v_mfma_f32_16x16x4_f32 v[20:23], v53, v37, v[20:23]
	v_mfma_f32_16x16x4_f32 v[16:19], v54, v38, v[16:19]
	v_mfma_f32_16x16x4_f32 v[20:23], v55, v39, v[20:23]
	ds_read_b128 v[32:35], v4 offset:1152
	ds_read_b128 v[36:39], v4 offset:1168
	s_waitcnt vmcnt(23)
	v_lshlrev_b32_e32 v40, 16, v96
	v_and_b32_e32 v41, 0xffff0000, v96
	v_lshlrev_b32_e32 v42, 16, v97
	v_and_b32_e32 v43, 0xffff0000, v97
	v_lshlrev_b32_e32 v44, 16, v98
	v_and_b32_e32 v45, 0xffff0000, v98
	v_lshlrev_b32_e32 v46, 16, v99
	v_and_b32_e32 v47, 0xffff0000, v99
	s_waitcnt lgkmcnt(2)
	v_mfma_f32_16x16x4_f32 v[16:19], v40, v24, v[16:19]
	v_mfma_f32_16x16x4_f32 v[20:23], v41, v25, v[20:23]
	v_mfma_f32_16x16x4_f32 v[16:19], v42, v26, v[16:19]
	v_mfma_f32_16x16x4_f32 v[20:23], v43, v27, v[20:23]
	v_mfma_f32_16x16x4_f32 v[16:19], v44, v28, v[16:19]
	v_mfma_f32_16x16x4_f32 v[20:23], v45, v29, v[20:23]
	v_mfma_f32_16x16x4_f32 v[16:19], v46, v30, v[16:19]
	v_mfma_f32_16x16x4_f32 v[20:23], v47, v31, v[20:23]
	ds_read_b128 v[24:27], v4 offset:1280
	ds_read_b128 v[28:31], v4 offset:1296
	s_waitcnt vmcnt(22)
	v_lshlrev_b32_e32 v48, 16, v100
	v_and_b32_e32 v49, 0xffff0000, v100
	v_lshlrev_b32_e32 v50, 16, v101
	v_and_b32_e32 v51, 0xffff0000, v101
	v_lshlrev_b32_e32 v52, 16, v102
	v_and_b32_e32 v53, 0xffff0000, v102
	v_lshlrev_b32_e32 v54, 16, v103
	v_and_b32_e32 v55, 0xffff0000, v103
	s_waitcnt lgkmcnt(2)
	v_mfma_f32_16x16x4_f32 v[16:19], v48, v32, v[16:19]
	v_mfma_f32_16x16x4_f32 v[20:23], v49, v33, v[20:23]
	v_mfma_f32_16x16x4_f32 v[16:19], v50, v34, v[16:19]
	v_mfma_f32_16x16x4_f32 v[20:23], v51, v35, v[20:23]
	v_mfma_f32_16x16x4_f32 v[16:19], v52, v36, v[16:19]
	v_mfma_f32_16x16x4_f32 v[20:23], v53, v37, v[20:23]
	v_mfma_f32_16x16x4_f32 v[16:19], v54, v38, v[16:19]
	v_mfma_f32_16x16x4_f32 v[20:23], v55, v39, v[20:23]
	ds_read_b128 v[32:35], v4 offset:1408
	ds_read_b128 v[36:39], v4 offset:1424
	s_waitcnt vmcnt(21)
	v_lshlrev_b32_e32 v40, 16, v104
	v_and_b32_e32 v41, 0xffff0000, v104
	v_lshlrev_b32_e32 v42, 16, v105
	v_and_b32_e32 v43, 0xffff0000, v105
	v_lshlrev_b32_e32 v44, 16, v106
	v_and_b32_e32 v45, 0xffff0000, v106
	v_lshlrev_b32_e32 v46, 16, v107
	v_and_b32_e32 v47, 0xffff0000, v107
	s_waitcnt lgkmcnt(2)
	v_mfma_f32_16x16x4_f32 v[16:19], v40, v24, v[16:19]
	v_mfma_f32_16x16x4_f32 v[20:23], v41, v25, v[20:23]
	v_mfma_f32_16x16x4_f32 v[16:19], v42, v26, v[16:19]
	v_mfma_f32_16x16x4_f32 v[20:23], v43, v27, v[20:23]
	v_mfma_f32_16x16x4_f32 v[16:19], v44, v28, v[16:19]
	v_mfma_f32_16x16x4_f32 v[20:23], v45, v29, v[20:23]
	v_mfma_f32_16x16x4_f32 v[16:19], v46, v30, v[16:19]
	v_mfma_f32_16x16x4_f32 v[20:23], v47, v31, v[20:23]
	ds_read_b128 v[24:27], v4 offset:1536
	ds_read_b128 v[28:31], v4 offset:1552
	s_waitcnt vmcnt(20)
	v_lshlrev_b32_e32 v48, 16, v108
	v_and_b32_e32 v49, 0xffff0000, v108
	v_lshlrev_b32_e32 v50, 16, v109
	v_and_b32_e32 v51, 0xffff0000, v109
	v_lshlrev_b32_e32 v52, 16, v110
	v_and_b32_e32 v53, 0xffff0000, v110
	v_lshlrev_b32_e32 v54, 16, v111
	v_and_b32_e32 v55, 0xffff0000, v111
	s_waitcnt lgkmcnt(2)
	v_mfma_f32_16x16x4_f32 v[16:19], v48, v32, v[16:19]
	v_mfma_f32_16x16x4_f32 v[20:23], v49, v33, v[20:23]
	v_mfma_f32_16x16x4_f32 v[16:19], v50, v34, v[16:19]
	v_mfma_f32_16x16x4_f32 v[20:23], v51, v35, v[20:23]
	v_mfma_f32_16x16x4_f32 v[16:19], v52, v36, v[16:19]
	v_mfma_f32_16x16x4_f32 v[20:23], v53, v37, v[20:23]
	v_mfma_f32_16x16x4_f32 v[16:19], v54, v38, v[16:19]
	v_mfma_f32_16x16x4_f32 v[20:23], v55, v39, v[20:23]
	ds_read_b128 v[32:35], v4 offset:1664
	ds_read_b128 v[36:39], v4 offset:1680
	s_waitcnt vmcnt(19)
	v_lshlrev_b32_e32 v40, 16, v112
	v_and_b32_e32 v41, 0xffff0000, v112
	v_lshlrev_b32_e32 v42, 16, v113
	v_and_b32_e32 v43, 0xffff0000, v113
	v_lshlrev_b32_e32 v44, 16, v114
	v_and_b32_e32 v45, 0xffff0000, v114
	v_lshlrev_b32_e32 v46, 16, v115
	v_and_b32_e32 v47, 0xffff0000, v115
	s_waitcnt lgkmcnt(2)
	v_mfma_f32_16x16x4_f32 v[16:19], v40, v24, v[16:19]
	v_mfma_f32_16x16x4_f32 v[20:23], v41, v25, v[20:23]
	v_mfma_f32_16x16x4_f32 v[16:19], v42, v26, v[16:19]
	v_mfma_f32_16x16x4_f32 v[20:23], v43, v27, v[20:23]
	v_mfma_f32_16x16x4_f32 v[16:19], v44, v28, v[16:19]
	v_mfma_f32_16x16x4_f32 v[20:23], v45, v29, v[20:23]
	v_mfma_f32_16x16x4_f32 v[16:19], v46, v30, v[16:19]
	v_mfma_f32_16x16x4_f32 v[20:23], v47, v31, v[20:23]
	ds_read_b128 v[24:27], v4 offset:1792
	ds_read_b128 v[28:31], v4 offset:1808
	s_waitcnt vmcnt(18)
	v_lshlrev_b32_e32 v48, 16, v116
	v_and_b32_e32 v49, 0xffff0000, v116
	v_lshlrev_b32_e32 v50, 16, v117
	v_and_b32_e32 v51, 0xffff0000, v117
	v_lshlrev_b32_e32 v52, 16, v118
	v_and_b32_e32 v53, 0xffff0000, v118
	v_lshlrev_b32_e32 v54, 16, v119
	v_and_b32_e32 v55, 0xffff0000, v119
	s_waitcnt lgkmcnt(2)
	v_mfma_f32_16x16x4_f32 v[16:19], v48, v32, v[16:19]
	v_mfma_f32_16x16x4_f32 v[20:23], v49, v33, v[20:23]
	v_mfma_f32_16x16x4_f32 v[16:19], v50, v34, v[16:19]
	v_mfma_f32_16x16x4_f32 v[20:23], v51, v35, v[20:23]
	v_mfma_f32_16x16x4_f32 v[16:19], v52, v36, v[16:19]
	v_mfma_f32_16x16x4_f32 v[20:23], v53, v37, v[20:23]
	v_mfma_f32_16x16x4_f32 v[16:19], v54, v38, v[16:19]
	v_mfma_f32_16x16x4_f32 v[20:23], v55, v39, v[20:23]
	ds_read_b128 v[32:35], v4 offset:1920
	ds_read_b128 v[36:39], v4 offset:1936
	s_waitcnt vmcnt(17)
	v_lshlrev_b32_e32 v40, 16, v120
	v_and_b32_e32 v41, 0xffff0000, v120
	v_lshlrev_b32_e32 v42, 16, v121
	v_and_b32_e32 v43, 0xffff0000, v121
	v_lshlrev_b32_e32 v44, 16, v122
	v_and_b32_e32 v45, 0xffff0000, v122
	v_lshlrev_b32_e32 v46, 16, v123
	v_and_b32_e32 v47, 0xffff0000, v123
	s_waitcnt lgkmcnt(2)
	v_mfma_f32_16x16x4_f32 v[16:19], v40, v24, v[16:19]
	v_mfma_f32_16x16x4_f32 v[20:23], v41, v25, v[20:23]
	v_mfma_f32_16x16x4_f32 v[16:19], v42, v26, v[16:19]
	v_mfma_f32_16x16x4_f32 v[20:23], v43, v27, v[20:23]
	v_mfma_f32_16x16x4_f32 v[16:19], v44, v28, v[16:19]
	v_mfma_f32_16x16x4_f32 v[20:23], v45, v29, v[20:23]
	v_mfma_f32_16x16x4_f32 v[16:19], v46, v30, v[16:19]
	v_mfma_f32_16x16x4_f32 v[20:23], v47, v31, v[20:23]
	ds_read_b128 v[24:27], v4 offset:2048
	ds_read_b128 v[28:31], v4 offset:2064
	s_waitcnt vmcnt(16)
	v_lshlrev_b32_e32 v48, 16, v124
	v_and_b32_e32 v49, 0xffff0000, v124
	v_lshlrev_b32_e32 v50, 16, v125
	v_and_b32_e32 v51, 0xffff0000, v125
	v_lshlrev_b32_e32 v52, 16, v126
	v_and_b32_e32 v53, 0xffff0000, v126
	v_lshlrev_b32_e32 v54, 16, v127
	v_and_b32_e32 v55, 0xffff0000, v127
	s_waitcnt lgkmcnt(2)
	v_mfma_f32_16x16x4_f32 v[16:19], v48, v32, v[16:19]
	v_mfma_f32_16x16x4_f32 v[20:23], v49, v33, v[20:23]
	v_mfma_f32_16x16x4_f32 v[16:19], v50, v34, v[16:19]
	v_mfma_f32_16x16x4_f32 v[20:23], v51, v35, v[20:23]
	v_mfma_f32_16x16x4_f32 v[16:19], v52, v36, v[16:19]
	v_mfma_f32_16x16x4_f32 v[20:23], v53, v37, v[20:23]
	v_mfma_f32_16x16x4_f32 v[16:19], v54, v38, v[16:19]
	v_mfma_f32_16x16x4_f32 v[20:23], v55, v39, v[20:23]
	ds_read_b128 v[32:35], v4 offset:2176
	ds_read_b128 v[36:39], v4 offset:2192
	s_waitcnt vmcnt(15)
	v_lshlrev_b32_e32 v40, 16, v128
	v_and_b32_e32 v41, 0xffff0000, v128
	v_lshlrev_b32_e32 v42, 16, v129
	v_and_b32_e32 v43, 0xffff0000, v129
	v_lshlrev_b32_e32 v44, 16, v130
	v_and_b32_e32 v45, 0xffff0000, v130
	v_lshlrev_b32_e32 v46, 16, v131
	v_and_b32_e32 v47, 0xffff0000, v131
	s_waitcnt lgkmcnt(2)
	v_mfma_f32_16x16x4_f32 v[16:19], v40, v24, v[16:19]
	v_mfma_f32_16x16x4_f32 v[20:23], v41, v25, v[20:23]
	v_mfma_f32_16x16x4_f32 v[16:19], v42, v26, v[16:19]
	v_mfma_f32_16x16x4_f32 v[20:23], v43, v27, v[20:23]
	v_mfma_f32_16x16x4_f32 v[16:19], v44, v28, v[16:19]
	v_mfma_f32_16x16x4_f32 v[20:23], v45, v29, v[20:23]
	v_mfma_f32_16x16x4_f32 v[16:19], v46, v30, v[16:19]
	v_mfma_f32_16x16x4_f32 v[20:23], v47, v31, v[20:23]
	ds_read_b128 v[24:27], v4 offset:2304
	ds_read_b128 v[28:31], v4 offset:2320
	s_waitcnt vmcnt(14)
	v_lshlrev_b32_e32 v48, 16, v132
	v_and_b32_e32 v49, 0xffff0000, v132
	v_lshlrev_b32_e32 v50, 16, v133
	v_and_b32_e32 v51, 0xffff0000, v133
	v_lshlrev_b32_e32 v52, 16, v134
	v_and_b32_e32 v53, 0xffff0000, v134
	v_lshlrev_b32_e32 v54, 16, v135
	v_and_b32_e32 v55, 0xffff0000, v135
	s_waitcnt lgkmcnt(2)
	v_mfma_f32_16x16x4_f32 v[16:19], v48, v32, v[16:19]
	v_mfma_f32_16x16x4_f32 v[20:23], v49, v33, v[20:23]
	v_mfma_f32_16x16x4_f32 v[16:19], v50, v34, v[16:19]
	v_mfma_f32_16x16x4_f32 v[20:23], v51, v35, v[20:23]
	v_mfma_f32_16x16x4_f32 v[16:19], v52, v36, v[16:19]
	v_mfma_f32_16x16x4_f32 v[20:23], v53, v37, v[20:23]
	v_mfma_f32_16x16x4_f32 v[16:19], v54, v38, v[16:19]
	v_mfma_f32_16x16x4_f32 v[20:23], v55, v39, v[20:23]
	ds_read_b128 v[32:35], v4 offset:2432
	ds_read_b128 v[36:39], v4 offset:2448
	s_waitcnt vmcnt(13)
	v_lshlrev_b32_e32 v40, 16, v136
	v_and_b32_e32 v41, 0xffff0000, v136
	v_lshlrev_b32_e32 v42, 16, v137
	v_and_b32_e32 v43, 0xffff0000, v137
	v_lshlrev_b32_e32 v44, 16, v138
	v_and_b32_e32 v45, 0xffff0000, v138
	v_lshlrev_b32_e32 v46, 16, v139
	v_and_b32_e32 v47, 0xffff0000, v139
	s_waitcnt lgkmcnt(2)
	v_mfma_f32_16x16x4_f32 v[16:19], v40, v24, v[16:19]
	v_mfma_f32_16x16x4_f32 v[20:23], v41, v25, v[20:23]
	v_mfma_f32_16x16x4_f32 v[16:19], v42, v26, v[16:19]
	v_mfma_f32_16x16x4_f32 v[20:23], v43, v27, v[20:23]
	v_mfma_f32_16x16x4_f32 v[16:19], v44, v28, v[16:19]
	v_mfma_f32_16x16x4_f32 v[20:23], v45, v29, v[20:23]
	v_mfma_f32_16x16x4_f32 v[16:19], v46, v30, v[16:19]
	v_mfma_f32_16x16x4_f32 v[20:23], v47, v31, v[20:23]
	ds_read_b128 v[24:27], v4 offset:2560
	ds_read_b128 v[28:31], v4 offset:2576
	s_waitcnt vmcnt(12)
	v_lshlrev_b32_e32 v48, 16, v140
	v_and_b32_e32 v49, 0xffff0000, v140
	v_lshlrev_b32_e32 v50, 16, v141
	v_and_b32_e32 v51, 0xffff0000, v141
	v_lshlrev_b32_e32 v52, 16, v142
	v_and_b32_e32 v53, 0xffff0000, v142
	v_lshlrev_b32_e32 v54, 16, v143
	v_and_b32_e32 v55, 0xffff0000, v143
	s_waitcnt lgkmcnt(2)
	v_mfma_f32_16x16x4_f32 v[16:19], v48, v32, v[16:19]
	v_mfma_f32_16x16x4_f32 v[20:23], v49, v33, v[20:23]
	v_mfma_f32_16x16x4_f32 v[16:19], v50, v34, v[16:19]
	v_mfma_f32_16x16x4_f32 v[20:23], v51, v35, v[20:23]
	v_mfma_f32_16x16x4_f32 v[16:19], v52, v36, v[16:19]
	v_mfma_f32_16x16x4_f32 v[20:23], v53, v37, v[20:23]
	v_mfma_f32_16x16x4_f32 v[16:19], v54, v38, v[16:19]
	v_mfma_f32_16x16x4_f32 v[20:23], v55, v39, v[20:23]
	ds_read_b128 v[32:35], v4 offset:2688
	ds_read_b128 v[36:39], v4 offset:2704
	s_waitcnt vmcnt(11)
	v_lshlrev_b32_e32 v40, 16, v144
	v_and_b32_e32 v41, 0xffff0000, v144
	v_lshlrev_b32_e32 v42, 16, v145
	v_and_b32_e32 v43, 0xffff0000, v145
	v_lshlrev_b32_e32 v44, 16, v146
	v_and_b32_e32 v45, 0xffff0000, v146
	v_lshlrev_b32_e32 v46, 16, v147
	v_and_b32_e32 v47, 0xffff0000, v147
	s_waitcnt lgkmcnt(2)
	v_mfma_f32_16x16x4_f32 v[16:19], v40, v24, v[16:19]
	v_mfma_f32_16x16x4_f32 v[20:23], v41, v25, v[20:23]
	v_mfma_f32_16x16x4_f32 v[16:19], v42, v26, v[16:19]
	v_mfma_f32_16x16x4_f32 v[20:23], v43, v27, v[20:23]
	v_mfma_f32_16x16x4_f32 v[16:19], v44, v28, v[16:19]
	v_mfma_f32_16x16x4_f32 v[20:23], v45, v29, v[20:23]
	v_mfma_f32_16x16x4_f32 v[16:19], v46, v30, v[16:19]
	v_mfma_f32_16x16x4_f32 v[20:23], v47, v31, v[20:23]
	ds_read_b128 v[24:27], v4 offset:2816
	ds_read_b128 v[28:31], v4 offset:2832
	s_waitcnt vmcnt(10)
	v_lshlrev_b32_e32 v48, 16, v148
	v_and_b32_e32 v49, 0xffff0000, v148
	v_lshlrev_b32_e32 v50, 16, v149
	v_and_b32_e32 v51, 0xffff0000, v149
	v_lshlrev_b32_e32 v52, 16, v150
	v_and_b32_e32 v53, 0xffff0000, v150
	v_lshlrev_b32_e32 v54, 16, v151
	v_and_b32_e32 v55, 0xffff0000, v151
	s_waitcnt lgkmcnt(2)
	v_mfma_f32_16x16x4_f32 v[16:19], v48, v32, v[16:19]
	v_mfma_f32_16x16x4_f32 v[20:23], v49, v33, v[20:23]
	v_mfma_f32_16x16x4_f32 v[16:19], v50, v34, v[16:19]
	v_mfma_f32_16x16x4_f32 v[20:23], v51, v35, v[20:23]
	v_mfma_f32_16x16x4_f32 v[16:19], v52, v36, v[16:19]
	v_mfma_f32_16x16x4_f32 v[20:23], v53, v37, v[20:23]
	v_mfma_f32_16x16x4_f32 v[16:19], v54, v38, v[16:19]
	v_mfma_f32_16x16x4_f32 v[20:23], v55, v39, v[20:23]
	ds_read_b128 v[32:35], v4 offset:2944
	ds_read_b128 v[36:39], v4 offset:2960
	s_waitcnt vmcnt(9)
	v_lshlrev_b32_e32 v40, 16, v152
	v_and_b32_e32 v41, 0xffff0000, v152
	v_lshlrev_b32_e32 v42, 16, v153
	v_and_b32_e32 v43, 0xffff0000, v153
	v_lshlrev_b32_e32 v44, 16, v154
	v_and_b32_e32 v45, 0xffff0000, v154
	v_lshlrev_b32_e32 v46, 16, v155
	v_and_b32_e32 v47, 0xffff0000, v155
	s_waitcnt lgkmcnt(2)
	v_mfma_f32_16x16x4_f32 v[16:19], v40, v24, v[16:19]
	v_mfma_f32_16x16x4_f32 v[20:23], v41, v25, v[20:23]
	v_mfma_f32_16x16x4_f32 v[16:19], v42, v26, v[16:19]
	v_mfma_f32_16x16x4_f32 v[20:23], v43, v27, v[20:23]
	v_mfma_f32_16x16x4_f32 v[16:19], v44, v28, v[16:19]
	v_mfma_f32_16x16x4_f32 v[20:23], v45, v29, v[20:23]
	v_mfma_f32_16x16x4_f32 v[16:19], v46, v30, v[16:19]
	v_mfma_f32_16x16x4_f32 v[20:23], v47, v31, v[20:23]
	ds_read_b128 v[24:27], v4 offset:3072
	ds_read_b128 v[28:31], v4 offset:3088
	s_waitcnt vmcnt(8)
	v_lshlrev_b32_e32 v48, 16, v156
	v_and_b32_e32 v49, 0xffff0000, v156
	v_lshlrev_b32_e32 v50, 16, v157
	v_and_b32_e32 v51, 0xffff0000, v157
	v_lshlrev_b32_e32 v52, 16, v158
	v_and_b32_e32 v53, 0xffff0000, v158
	v_lshlrev_b32_e32 v54, 16, v159
	v_and_b32_e32 v55, 0xffff0000, v159
	s_waitcnt lgkmcnt(2)
	v_mfma_f32_16x16x4_f32 v[16:19], v48, v32, v[16:19]
	v_mfma_f32_16x16x4_f32 v[20:23], v49, v33, v[20:23]
	v_mfma_f32_16x16x4_f32 v[16:19], v50, v34, v[16:19]
	v_mfma_f32_16x16x4_f32 v[20:23], v51, v35, v[20:23]
	v_mfma_f32_16x16x4_f32 v[16:19], v52, v36, v[16:19]
	v_mfma_f32_16x16x4_f32 v[20:23], v53, v37, v[20:23]
	v_mfma_f32_16x16x4_f32 v[16:19], v54, v38, v[16:19]
	v_mfma_f32_16x16x4_f32 v[20:23], v55, v39, v[20:23]
	ds_read_b128 v[32:35], v4 offset:3200
	ds_read_b128 v[36:39], v4 offset:3216
	s_waitcnt vmcnt(7)
	v_lshlrev_b32_e32 v40, 16, v160
	v_and_b32_e32 v41, 0xffff0000, v160
	v_lshlrev_b32_e32 v42, 16, v161
	v_and_b32_e32 v43, 0xffff0000, v161
	v_lshlrev_b32_e32 v44, 16, v162
	v_and_b32_e32 v45, 0xffff0000, v162
	v_lshlrev_b32_e32 v46, 16, v163
	v_and_b32_e32 v47, 0xffff0000, v163
	s_waitcnt lgkmcnt(2)
	v_mfma_f32_16x16x4_f32 v[16:19], v40, v24, v[16:19]
	v_mfma_f32_16x16x4_f32 v[20:23], v41, v25, v[20:23]
	v_mfma_f32_16x16x4_f32 v[16:19], v42, v26, v[16:19]
	v_mfma_f32_16x16x4_f32 v[20:23], v43, v27, v[20:23]
	v_mfma_f32_16x16x4_f32 v[16:19], v44, v28, v[16:19]
	v_mfma_f32_16x16x4_f32 v[20:23], v45, v29, v[20:23]
	v_mfma_f32_16x16x4_f32 v[16:19], v46, v30, v[16:19]
	v_mfma_f32_16x16x4_f32 v[20:23], v47, v31, v[20:23]
	ds_read_b128 v[24:27], v4 offset:3328
	ds_read_b128 v[28:31], v4 offset:3344
	s_waitcnt vmcnt(6)
	v_lshlrev_b32_e32 v48, 16, v164
	v_and_b32_e32 v49, 0xffff0000, v164
	v_lshlrev_b32_e32 v50, 16, v165
	v_and_b32_e32 v51, 0xffff0000, v165
	v_lshlrev_b32_e32 v52, 16, v166
	v_and_b32_e32 v53, 0xffff0000, v166
	v_lshlrev_b32_e32 v54, 16, v167
	v_and_b32_e32 v55, 0xffff0000, v167
	s_waitcnt lgkmcnt(2)
	v_mfma_f32_16x16x4_f32 v[16:19], v48, v32, v[16:19]
	v_mfma_f32_16x16x4_f32 v[20:23], v49, v33, v[20:23]
	v_mfma_f32_16x16x4_f32 v[16:19], v50, v34, v[16:19]
	v_mfma_f32_16x16x4_f32 v[20:23], v51, v35, v[20:23]
	v_mfma_f32_16x16x4_f32 v[16:19], v52, v36, v[16:19]
	v_mfma_f32_16x16x4_f32 v[20:23], v53, v37, v[20:23]
	v_mfma_f32_16x16x4_f32 v[16:19], v54, v38, v[16:19]
	v_mfma_f32_16x16x4_f32 v[20:23], v55, v39, v[20:23]
	ds_read_b128 v[32:35], v4 offset:3456
	ds_read_b128 v[36:39], v4 offset:3472
	s_waitcnt vmcnt(5)
	v_lshlrev_b32_e32 v40, 16, v168
	v_and_b32_e32 v41, 0xffff0000, v168
	v_lshlrev_b32_e32 v42, 16, v169
	v_and_b32_e32 v43, 0xffff0000, v169
	v_lshlrev_b32_e32 v44, 16, v170
	v_and_b32_e32 v45, 0xffff0000, v170
	v_lshlrev_b32_e32 v46, 16, v171
	v_and_b32_e32 v47, 0xffff0000, v171
	s_waitcnt lgkmcnt(2)
	v_mfma_f32_16x16x4_f32 v[16:19], v40, v24, v[16:19]
	v_mfma_f32_16x16x4_f32 v[20:23], v41, v25, v[20:23]
	v_mfma_f32_16x16x4_f32 v[16:19], v42, v26, v[16:19]
	v_mfma_f32_16x16x4_f32 v[20:23], v43, v27, v[20:23]
	v_mfma_f32_16x16x4_f32 v[16:19], v44, v28, v[16:19]
	v_mfma_f32_16x16x4_f32 v[20:23], v45, v29, v[20:23]
	v_mfma_f32_16x16x4_f32 v[16:19], v46, v30, v[16:19]
	v_mfma_f32_16x16x4_f32 v[20:23], v47, v31, v[20:23]
	ds_read_b128 v[24:27], v4 offset:3584
	ds_read_b128 v[28:31], v4 offset:3600
	s_waitcnt vmcnt(4)
	v_lshlrev_b32_e32 v48, 16, v172
	v_and_b32_e32 v49, 0xffff0000, v172
	v_lshlrev_b32_e32 v50, 16, v173
	v_and_b32_e32 v51, 0xffff0000, v173
	v_lshlrev_b32_e32 v52, 16, v174
	v_and_b32_e32 v53, 0xffff0000, v174
	v_lshlrev_b32_e32 v54, 16, v175
	v_and_b32_e32 v55, 0xffff0000, v175
	s_waitcnt lgkmcnt(2)
	v_mfma_f32_16x16x4_f32 v[16:19], v48, v32, v[16:19]
	v_mfma_f32_16x16x4_f32 v[20:23], v49, v33, v[20:23]
	v_mfma_f32_16x16x4_f32 v[16:19], v50, v34, v[16:19]
	v_mfma_f32_16x16x4_f32 v[20:23], v51, v35, v[20:23]
	v_mfma_f32_16x16x4_f32 v[16:19], v52, v36, v[16:19]
	v_mfma_f32_16x16x4_f32 v[20:23], v53, v37, v[20:23]
	v_mfma_f32_16x16x4_f32 v[16:19], v54, v38, v[16:19]
	v_mfma_f32_16x16x4_f32 v[20:23], v55, v39, v[20:23]
	ds_read_b128 v[32:35], v4 offset:3712
	ds_read_b128 v[36:39], v4 offset:3728
	s_waitcnt vmcnt(3)
	v_lshlrev_b32_e32 v40, 16, v176
	v_and_b32_e32 v41, 0xffff0000, v176
	v_lshlrev_b32_e32 v42, 16, v177
	v_and_b32_e32 v43, 0xffff0000, v177
	v_lshlrev_b32_e32 v44, 16, v178
	v_and_b32_e32 v45, 0xffff0000, v178
	v_lshlrev_b32_e32 v46, 16, v179
	v_and_b32_e32 v47, 0xffff0000, v179
	s_waitcnt lgkmcnt(2)
	v_mfma_f32_16x16x4_f32 v[16:19], v40, v24, v[16:19]
	v_mfma_f32_16x16x4_f32 v[20:23], v41, v25, v[20:23]
	v_mfma_f32_16x16x4_f32 v[16:19], v42, v26, v[16:19]
	v_mfma_f32_16x16x4_f32 v[20:23], v43, v27, v[20:23]
	v_mfma_f32_16x16x4_f32 v[16:19], v44, v28, v[16:19]
	v_mfma_f32_16x16x4_f32 v[20:23], v45, v29, v[20:23]
	v_mfma_f32_16x16x4_f32 v[16:19], v46, v30, v[16:19]
	v_mfma_f32_16x16x4_f32 v[20:23], v47, v31, v[20:23]
	ds_read_b128 v[24:27], v4 offset:3840
	ds_read_b128 v[28:31], v4 offset:3856
	s_waitcnt vmcnt(2)
	v_lshlrev_b32_e32 v48, 16, v180
	v_and_b32_e32 v49, 0xffff0000, v180
	v_lshlrev_b32_e32 v50, 16, v181
	v_and_b32_e32 v51, 0xffff0000, v181
	v_lshlrev_b32_e32 v52, 16, v182
	v_and_b32_e32 v53, 0xffff0000, v182
	v_lshlrev_b32_e32 v54, 16, v183
	v_and_b32_e32 v55, 0xffff0000, v183
	s_waitcnt lgkmcnt(2)
	v_mfma_f32_16x16x4_f32 v[16:19], v48, v32, v[16:19]
	v_mfma_f32_16x16x4_f32 v[20:23], v49, v33, v[20:23]
	v_mfma_f32_16x16x4_f32 v[16:19], v50, v34, v[16:19]
	v_mfma_f32_16x16x4_f32 v[20:23], v51, v35, v[20:23]
	v_mfma_f32_16x16x4_f32 v[16:19], v52, v36, v[16:19]
	v_mfma_f32_16x16x4_f32 v[20:23], v53, v37, v[20:23]
	v_mfma_f32_16x16x4_f32 v[16:19], v54, v38, v[16:19]
	v_mfma_f32_16x16x4_f32 v[20:23], v55, v39, v[20:23]
	ds_read_b128 v[32:35], v4 offset:3968
	ds_read_b128 v[36:39], v4 offset:3984
	s_waitcnt vmcnt(1)
	v_lshlrev_b32_e32 v40, 16, v184
	v_and_b32_e32 v41, 0xffff0000, v184
	v_lshlrev_b32_e32 v42, 16, v185
	v_and_b32_e32 v43, 0xffff0000, v185
	v_lshlrev_b32_e32 v44, 16, v186
	v_and_b32_e32 v45, 0xffff0000, v186
	v_lshlrev_b32_e32 v46, 16, v187
	v_and_b32_e32 v47, 0xffff0000, v187
	s_waitcnt lgkmcnt(2)
	v_mfma_f32_16x16x4_f32 v[16:19], v40, v24, v[16:19]
	v_mfma_f32_16x16x4_f32 v[20:23], v41, v25, v[20:23]
	v_mfma_f32_16x16x4_f32 v[16:19], v42, v26, v[16:19]
	v_mfma_f32_16x16x4_f32 v[20:23], v43, v27, v[20:23]
	v_mfma_f32_16x16x4_f32 v[16:19], v44, v28, v[16:19]
	v_mfma_f32_16x16x4_f32 v[20:23], v45, v29, v[20:23]
	v_mfma_f32_16x16x4_f32 v[16:19], v46, v30, v[16:19]
	v_mfma_f32_16x16x4_f32 v[20:23], v47, v31, v[20:23]
	s_waitcnt vmcnt(0)
	v_lshlrev_b32_e32 v48, 16, v188
	v_and_b32_e32 v49, 0xffff0000, v188
	v_lshlrev_b32_e32 v50, 16, v189
	v_and_b32_e32 v51, 0xffff0000, v189
	v_lshlrev_b32_e32 v52, 16, v190
	v_and_b32_e32 v53, 0xffff0000, v190
	v_lshlrev_b32_e32 v54, 16, v191
	v_and_b32_e32 v55, 0xffff0000, v191
	s_waitcnt lgkmcnt(0)
	v_mfma_f32_16x16x4_f32 v[16:19], v48, v32, v[16:19]
	v_mfma_f32_16x16x4_f32 v[20:23], v49, v33, v[20:23]
	v_mfma_f32_16x16x4_f32 v[16:19], v50, v34, v[16:19]
	v_mfma_f32_16x16x4_f32 v[20:23], v51, v35, v[20:23]
	v_mfma_f32_16x16x4_f32 v[16:19], v52, v36, v[16:19]
	v_mfma_f32_16x16x4_f32 v[20:23], v53, v37, v[20:23]
	v_mfma_f32_16x16x4_f32 v[16:19], v54, v38, v[16:19]
	v_mfma_f32_16x16x4_f32 v[20:23], v55, v39, v[20:23]
	s_nop 7
	s_nop 7
	v_add_f32_e32 v16, v16, v20
	v_add_f32_e32 v17, v17, v21
	v_add_f32_e32 v18, v18, v22
	v_add_f32_e32 v19, v19, v23
	ds_bpermute_b32 v60, v8, v56
	ds_bpermute_b32 v61, v8, v57
	ds_bpermute_b32 v62, v8, v58
	ds_bpermute_b32 v63, v8, v59
	s_waitcnt lgkmcnt(0)
	v_add_f32_e32 v56, v56, v60
	v_add_f32_e32 v57, v57, v61
	v_add_f32_e32 v58, v58, v62
	v_add_f32_e32 v59, v59, v63
	s_nop 0
	ds_bpermute_b32 v60, v9, v56
	ds_bpermute_b32 v61, v9, v57
	ds_bpermute_b32 v62, v9, v58
	ds_bpermute_b32 v63, v9, v59
	s_waitcnt lgkmcnt(0)
	v_add_f32_e32 v56, v56, v60
	v_add_f32_e32 v57, v57, v61
	v_add_f32_e32 v58, v58, v62
	v_add_f32_e32 v59, v59, v63
	s_nop 0
	ds_bpermute_b32 v60, v10, v56
	ds_bpermute_b32 v61, v10, v57
	ds_bpermute_b32 v62, v10, v58
	ds_bpermute_b32 v63, v10, v59
	s_waitcnt lgkmcnt(0)
	v_add_f32_e32 v56, v56, v60
	v_add_f32_e32 v57, v57, v61
	v_add_f32_e32 v58, v58, v62
	v_add_f32_e32 v59, v59, v63
	s_nop 0
	ds_bpermute_b32 v60, v11, v56
	ds_bpermute_b32 v61, v11, v57
	ds_bpermute_b32 v62, v11, v58
	ds_bpermute_b32 v63, v11, v59
	s_waitcnt lgkmcnt(0)
	v_add_f32_e32 v56, v56, v60
	v_add_f32_e32 v57, v57, v61
	v_add_f32_e32 v58, v58, v62
	v_add_f32_e32 v59, v59, v63
	s_nop 0
	v_mov_b32_e32 v60, 0x358637bd
	s_mov_b32 s32, 0x3a800000
	v_fma_f32 v56, v56, s32, v60
	v_fma_f32 v57, v57, s32, v60
	v_fma_f32 v58, v58, s32, v60
	v_fma_f32 v59, v59, s32, v60
	v_rsq_f32_e32 v56, v56
	v_rsq_f32_e32 v57, v57
	v_rsq_f32_e32 v58, v58
	v_rsq_f32_e32 v59, v59
	s_nop 0
	v_mul_f32_e32 v16, v16, v56
	v_mul_f32_e32 v17, v17, v57
	v_mul_f32_e32 v18, v18, v58
	v_mul_f32_e32 v19, v19, v59
	v_mul_f32_e32 v20, 0xbfb8aa3b, v16
	v_mul_f32_e32 v21, 0xbfb8aa3b, v17
	v_mul_f32_e32 v22, 0xbfb8aa3b, v18
	v_mul_f32_e32 v23, 0xbfb8aa3b, v19
	v_exp_f32_e32 v20, v20
	v_exp_f32_e32 v21, v21
	v_exp_f32_e32 v22, v22
	v_exp_f32_e32 v23, v23
	v_add_f32_e32 v16, v16, v6
	v_add_f32_e32 v17, v17, v6
	v_add_f32_e32 v18, v18, v6
	v_add_f32_e32 v19, v19, v6
	v_add_f32_e32 v20, 1.0, v20
	v_add_f32_e32 v21, 1.0, v21
	v_add_f32_e32 v22, 1.0, v22
	v_add_f32_e32 v23, 1.0, v23
	v_rcp_f32_e32 v20, v20
	v_rcp_f32_e32 v21, v21
	v_rcp_f32_e32 v22, v22
	v_rcp_f32_e32 v23, v23
	v_mul_f32_e32 v60, 0x3fb8aa3b, v16
	v_mul_f32_e32 v61, 0x3fb8aa3b, v17
	v_mul_f32_e32 v62, 0x3fb8aa3b, v18
	v_mul_f32_e32 v63, 0x3fb8aa3b, v19
	v_exp_f32_e32 v60, v60
	v_exp_f32_e32 v61, v61
	v_exp_f32_e32 v62, v62
	v_exp_f32_e32 v63, v63
	s_nop 0
	v_add_f32_e32 v56, 1.0, v60
	v_add_f32_e32 v57, 1.0, v61
	v_add_f32_e32 v58, 1.0, v62
	v_add_f32_e32 v59, 1.0, v63
	v_log_f32_e32 v56, v56
	v_log_f32_e32 v57, v57
	v_log_f32_e32 v58, v58
	v_log_f32_e32 v59, v59
	s_nop 0
	v_mul_f32_e32 v56, 0x3f317218, v56
	v_mul_f32_e32 v57, 0x3f317218, v57
	v_mul_f32_e32 v58, 0x3f317218, v58
	v_mul_f32_e32 v59, 0x3f317218, v59
	v_mov_b32_e32 v14, 0xc1200000
	v_mov_b32_e32 v15, 0x41a00000
	v_cmp_lt_f32_e64 vcc, v16, v14
	s_nop 1
	v_cndmask_b32_e64 v56, v56, v60, vcc
	v_cmp_gt_f32_e64 vcc, v16, v15
	s_nop 1
	v_cndmask_b32_e64 v56, v56, v16, vcc
	v_cmp_lt_f32_e64 vcc, v17, v14
	s_nop 1
	v_cndmask_b32_e64 v57, v57, v61, vcc
	v_cmp_gt_f32_e64 vcc, v17, v15
	s_nop 1
	v_cndmask_b32_e64 v57, v57, v17, vcc
	v_cmp_lt_f32_e64 vcc, v18, v14
	s_nop 1
	v_cndmask_b32_e64 v58, v58, v62, vcc
	v_cmp_gt_f32_e64 vcc, v18, v15
	s_nop 1
	v_cndmask_b32_e64 v58, v58, v18, vcc
	v_cmp_lt_f32_e64 vcc, v19, v14
	s_nop 1
	v_cndmask_b32_e64 v59, v59, v63, vcc
	v_cmp_gt_f32_e64 vcc, v19, v15
	s_nop 1
	v_cndmask_b32_e64 v59, v59, v19, vcc
	v_mul_f32_e32 v56, v56, v7
	v_mul_f32_e32 v57, v57, v7
	v_mul_f32_e32 v58, v58, v7
	v_mul_f32_e32 v59, v59, v7
	v_sub_f32_e32 v56, 0, v56
	v_sub_f32_e32 v57, 0, v57
	v_sub_f32_e32 v58, 0, v58
	v_sub_f32_e32 v59, 0, v59
	v_cndmask_b32_e64 v56, v56, v20, s[98:99]
	v_cndmask_b32_e64 v57, v57, v21, s[98:99]
	v_cndmask_b32_e64 v58, v58, v22, s[98:99]
	v_cndmask_b32_e64 v59, v59, v23, s[98:99]
	s_and_saveexec_b64 s[90:91], s[100:101]
	global_store_dword v13, v56, s[94:95]
	global_store_dword v13, v57, s[94:95] offset:32
	global_store_dword v13, v58, s[94:95] offset:64
	global_store_dword v13, v59, s[94:95] offset:96
	s_mov_b64 exec, s[90:91]
	s_add_u32 s87, s87, s34
	s_branch .Lbd_loop
.Lbd_done:
.LBB0_456:
	s_barrier
	s_waitcnt vmcnt(0) lgkmcnt(0)
	s_barrier
	s_waitcnt vmcnt(0)
	s_barrier
	s_and_saveexec_b64 s[10:11], s[4:5]
	s_cbranch_execz .LBB0_508
	s_add_i32 s12, 0, 0x27ff0
	v_mov_b32_e32 v0, s12
	s_waitcnt vmcnt(0) expcnt(0) lgkmcnt(0)
	ds_read_b32 v2, v0
	s_add_i32 s12, 0, 0x27ff4
	v_mov_b32_e32 v0, s12
	ds_read_b32 v0, v0
	s_waitcnt lgkmcnt(1)
	v_cmp_ne_u32_e32 vcc, 0, v2
	s_cbranch_vccnz .LBB0_472
	s_add_u32 s12, s38, 0x4200
	s_addc_u32 s13, s39, 0
	s_add_u32 s14, s38, 0x4400
	s_addc_u32 s15, s39, 0
	s_add_u32 s16, s38, 0x4500
	s_addc_u32 s17, s39, 0
	s_add_u32 s18, s38, 0x4600
	s_addc_u32 s19, s39, 0
	s_add_u32 s20, s38, 0x4700
	s_addc_u32 s21, s39, 0
	s_add_u32 s24, s38, 0x4800
	s_addc_u32 s25, s39, 0
	s_add_u32 s26, s38, 0x4900
	s_addc_u32 s27, s39, 0
	s_add_u32 s28, s38, 0x4a00
	s_addc_u32 s29, s39, 0
	s_add_u32 s30, s38, 0x4b00
	s_addc_u32 s31, s39, 0
	s_add_u32 s40, s38, 0x4c00
	s_addc_u32 s41, s39, 0
	s_add_u32 s42, s38, 0x4d00
	s_addc_u32 s43, s39, 0
	s_add_u32 s50, s38, 0x4e00
	s_addc_u32 s51, s39, 0
	s_add_u32 s52, s38, 0x4f00
	s_addc_u32 s53, s39, 0
	s_add_u32 s54, s38, 0x5000
	s_addc_u32 s55, s39, 0
	s_add_u32 s56, s38, 0x5100
	s_addc_u32 s57, s39, 0
	s_add_u32 s58, s38, 0x5200
	s_addc_u32 s59, s39, 0
	s_mul_i32 s35, s47, s85
	s_add_u32 s60, s38, 0x5300
	s_mul_i32 s35, s35, s46
	s_addc_u32 s61, s39, 0
	s_mov_b32 s68, 1
	v_mov_b32_e32 v16, 0
	s_branch .LBB0_460

.LBB0_904:
	v_lshrrev_b32_e32 v162, 6, v206
	v_and_b32_e32 v204, 63, v206
	v_lshrrev_b32_e32 v163, 2, v162
	v_and_b32_e32 v162, 3, v162
	v_lshlrev_b32_e32 v163, 6, v163
	v_lshrrev_b32_e32 v210, 4, v204
	v_and_b32_e32 v211, 15, v204
	v_add_u32_e32 v163, v163, v211
	s_lshl_b32 vcc_lo, s63, 8
	v_add_u32_e32 v163, vcc_lo, v163
	v_lshlrev_b32_e32 v204, 5, v162
	v_lshl_add_u32 v204, v210, 3, v204
	s_lshl_b32 vcc_lo, s64, 8
	v_add_u32_e32 v204, vcc_lo, v204
	v_mov_b32_e32 v205, 0x2c00
	v_mul_u32_u24_e32 v205, v163, v205
	v_lshl_add_u32 v205, v204, 1, v205
	s_add_u32 s88, s96, 0x11f00400
	s_addc_u32 s89, s97, 0
	s_add_u32 s92, s96, 0x11f00400
	s_addc_u32 s93, s97, 0
	s_add_u32 s100, s92, 0x1800
	s_addc_u32 s101, s93, 0
	global_load_dwordx4 v[128:131], v205, s[100:101]
	s_add_u32 s100, s92, 0x1800
	s_addc_u32 s101, s93, 0
	global_load_dwordx4 v[148:151], v205, s[100:101] offset:256
	s_add_u32 s92, s92, 0x2c000
	s_addc_u32 s93, s93, 0
	s_add_u32 s100, s92, 0x1800
	s_addc_u32 s101, s93, 0
	global_load_dwordx4 v[152:155], v205, s[100:101]
	s_add_u32 s100, s92, 0x1800
	s_addc_u32 s101, s93, 0
	global_load_dwordx4 v[164:167], v205, s[100:101] offset:256
	s_add_u32 s92, s92, 0x2c000
	s_addc_u32 s93, s93, 0
	s_add_u32 s100, s92, 0x1800
	s_addc_u32 s101, s93, 0
	global_load_dwordx4 v[168:171], v205, s[100:101]
	s_add_u32 s100, s92, 0x1800
	s_addc_u32 s101, s93, 0
	global_load_dwordx4 v[172:175], v205, s[100:101] offset:256
	s_add_u32 s92, s92, 0x2c000
	s_addc_u32 s93, s93, 0
	s_add_u32 s100, s92, 0x1800
	s_addc_u32 s101, s93, 0
	global_load_dwordx4 v[176:179], v205, s[100:101]
	s_add_u32 s100, s92, 0x1800
	s_addc_u32 s101, s93, 0
	global_load_dwordx4 v[180:183], v205, s[100:101] offset:256
	s_add_u32 s92, s92, 0xdc000
	s_addc_u32 s93, s93, 0
	s_add_u32 s100, s92, 0x1800
	s_addc_u32 s101, s93, 0
	global_load_dwordx4 v[184:187], v205, s[100:101]
	s_add_u32 s100, s92, 0x1800
	s_addc_u32 s101, s93, 0
	global_load_dwordx4 v[188:191], v205, s[100:101] offset:256
	s_add_u32 s92, s92, 0x2c000
	s_addc_u32 s93, s93, 0
	s_add_u32 s100, s92, 0x1800
	s_addc_u32 s101, s93, 0
	global_load_dwordx4 v[192:195], v205, s[100:101]
	s_add_u32 s100, s92, 0x1800
	s_addc_u32 s101, s93, 0
	global_load_dwordx4 v[196:199], v205, s[100:101] offset:256
	s_waitcnt vmcnt(11)
	v_lshlrev_b32_e32 v212, 16, v128
	v_and_b32_e32 v213, 0xffff0000, v128
	v_lshlrev_b32_e32 v214, 16, v129
	v_and_b32_e32 v215, 0xffff0000, v129
	v_lshlrev_b32_e32 v200, 16, v130
	v_and_b32_e32 v201, 0xffff0000, v130
	v_lshlrev_b32_e32 v202, 16, v131
	v_and_b32_e32 v203, 0xffff0000, v131
	v_mul_f32_e32 v212, 0xbfb8aa3b, v212
	v_mul_f32_e32 v213, 0xbfb8aa3b, v213
	v_mul_f32_e32 v214, 0xbfb8aa3b, v214
	v_mul_f32_e32 v215, 0xbfb8aa3b, v215
	v_mul_f32_e32 v200, 0xbfb8aa3b, v200
	v_mul_f32_e32 v201, 0xbfb8aa3b, v201
	v_mul_f32_e32 v202, 0xbfb8aa3b, v202
	v_mul_f32_e32 v203, 0xbfb8aa3b, v203
	v_exp_f32_e32 v212, v212
	v_exp_f32_e32 v213, v213
	v_exp_f32_e32 v214, v214
	v_exp_f32_e32 v215, v215
	v_exp_f32_e32 v200, v200
	v_exp_f32_e32 v201, v201
	v_exp_f32_e32 v202, v202
	v_exp_f32_e32 v203, v203
	s_nop 0
	v_add_f32_e32 v212, 1.0, v212
	v_add_f32_e32 v213, 1.0, v213
	v_add_f32_e32 v214, 1.0, v214
	v_add_f32_e32 v215, 1.0, v215
	v_add_f32_e32 v200, 1.0, v200
	v_add_f32_e32 v201, 1.0, v201
	v_add_f32_e32 v202, 1.0, v202
	v_add_f32_e32 v203, 1.0, v203
	v_rcp_f32_e32 v212, v212
	v_rcp_f32_e32 v213, v213
	v_rcp_f32_e32 v214, v214
	v_rcp_f32_e32 v215, v215
	v_rcp_f32_e32 v200, v200
	v_rcp_f32_e32 v201, v201
	v_rcp_f32_e32 v202, v202
	v_rcp_f32_e32 v203, v203
	s_nop 0
	v_mul_f32_e32 v124, v124, v212
	v_mul_f32_e32 v125, v125, v213
	v_mul_f32_e32 v126, v126, v214
	v_mul_f32_e32 v127, v127, v215
	v_mul_f32_e32 v120, v120, v200
	v_mul_f32_e32 v121, v121, v201
	v_mul_f32_e32 v122, v122, v202
	v_mul_f32_e32 v123, v123, v203
	v_cvt_pk_bf16_f32 v124, v124, v125
	v_cvt_pk_bf16_f32 v125, v126, v127
	v_cvt_pk_bf16_f32 v126, v120, v121
	v_cvt_pk_bf16_f32 v127, v122, v123
	global_store_dwordx4 v205, v[124:127], s[88:89]
	s_add_u32 s92, s92, 0x2c000
	s_addc_u32 s93, s93, 0
	s_add_u32 s100, s92, 0x1800
	s_addc_u32 s101, s93, 0
	global_load_dwordx4 v[128:131], v205, s[100:101]
	s_waitcnt vmcnt(12)
	v_lshlrev_b32_e32 v212, 16, v148
	v_and_b32_e32 v213, 0xffff0000, v148
	v_lshlrev_b32_e32 v214, 16, v149
	v_and_b32_e32 v215, 0xffff0000, v149
	v_lshlrev_b32_e32 v200, 16, v150
	v_and_b32_e32 v201, 0xffff0000, v150
	v_lshlrev_b32_e32 v202, 16, v151
	v_and_b32_e32 v203, 0xffff0000, v151
	v_mul_f32_e32 v212, 0xbfb8aa3b, v212
	v_mul_f32_e32 v213, 0xbfb8aa3b, v213
	v_mul_f32_e32 v214, 0xbfb8aa3b, v214
	v_mul_f32_e32 v215, 0xbfb8aa3b, v215
	v_mul_f32_e32 v200, 0xbfb8aa3b, v200
	v_mul_f32_e32 v201, 0xbfb8aa3b, v201
	v_mul_f32_e32 v202, 0xbfb8aa3b, v202
	v_mul_f32_e32 v203, 0xbfb8aa3b, v203
	v_exp_f32_e32 v212, v212
	v_exp_f32_e32 v213, v213
	v_exp_f32_e32 v214, v214
	v_exp_f32_e32 v215, v215
	v_exp_f32_e32 v200, v200
	v_exp_f32_e32 v201, v201
	v_exp_f32_e32 v202, v202
	v_exp_f32_e32 v203, v203
	s_nop 0
	v_add_f32_e32 v212, 1.0, v212
	v_add_f32_e32 v213, 1.0, v213
	v_add_f32_e32 v214, 1.0, v214
	v_add_f32_e32 v215, 1.0, v215
	v_add_f32_e32 v200, 1.0, v200
	v_add_f32_e32 v201, 1.0, v201
	v_add_f32_e32 v202, 1.0, v202
	v_add_f32_e32 v203, 1.0, v203
	v_rcp_f32_e32 v212, v212
	v_rcp_f32_e32 v213, v213
	v_rcp_f32_e32 v214, v214
	v_rcp_f32_e32 v215, v215
	v_rcp_f32_e32 v200, v200
	v_rcp_f32_e32 v201, v201
	v_rcp_f32_e32 v202, v202
	v_rcp_f32_e32 v203, v203
	s_nop 0
	v_mul_f32_e32 v116, v116, v212
	v_mul_f32_e32 v117, v117, v213
	v_mul_f32_e32 v118, v118, v214
	v_mul_f32_e32 v119, v119, v215
	v_mul_f32_e32 v112, v112, v200
	v_mul_f32_e32 v113, v113, v201
	v_mul_f32_e32 v114, v114, v202
	v_mul_f32_e32 v115, v115, v203
	v_cvt_pk_bf16_f32 v116, v116, v117
	v_cvt_pk_bf16_f32 v117, v118, v119
	v_cvt_pk_bf16_f32 v118, v112, v113
	v_cvt_pk_bf16_f32 v119, v114, v115
	global_store_dwordx4 v205, v[116:119], s[88:89] offset:256
	s_add_u32 s100, s92, 0x1800
	s_addc_u32 s101, s93, 0
	global_load_dwordx4 v[148:151], v205, s[100:101] offset:256
	s_add_u32 s88, s88, 0x2c000
	s_addc_u32 s89, s89, 0
	s_waitcnt vmcnt(13)
	v_lshlrev_b32_e32 v212, 16, v152
	v_and_b32_e32 v213, 0xffff0000, v152
	v_lshlrev_b32_e32 v214, 16, v153
	v_and_b32_e32 v215, 0xffff0000, v153
	v_lshlrev_b32_e32 v200, 16, v154
	v_and_b32_e32 v201, 0xffff0000, v154
	v_lshlrev_b32_e32 v202, 16, v155
	v_and_b32_e32 v203, 0xffff0000, v155
	v_mul_f32_e32 v212, 0xbfb8aa3b, v212
	v_mul_f32_e32 v213, 0xbfb8aa3b, v213
	v_mul_f32_e32 v214, 0xbfb8aa3b, v214
	v_mul_f32_e32 v215, 0xbfb8aa3b, v215
	v_mul_f32_e32 v200, 0xbfb8aa3b, v200
	v_mul_f32_e32 v201, 0xbfb8aa3b, v201
	v_mul_f32_e32 v202, 0xbfb8aa3b, v202
	v_mul_f32_e32 v203, 0xbfb8aa3b, v203
	v_exp_f32_e32 v212, v212
	v_exp_f32_e32 v213, v213
	v_exp_f32_e32 v214, v214
	v_exp_f32_e32 v215, v215
	v_exp_f32_e32 v200, v200
	v_exp_f32_e32 v201, v201
	v_exp_f32_e32 v202, v202
	v_exp_f32_e32 v203, v203
	s_nop 0
	v_add_f32_e32 v212, 1.0, v212
	v_add_f32_e32 v213, 1.0, v213
	v_add_f32_e32 v214, 1.0, v214
	v_add_f32_e32 v215, 1.0, v215
	v_add_f32_e32 v200, 1.0, v200
	v_add_f32_e32 v201, 1.0, v201
	v_add_f32_e32 v202, 1.0, v202
	v_add_f32_e32 v203, 1.0, v203
	v_rcp_f32_e32 v212, v212
	v_rcp_f32_e32 v213, v213
	v_rcp_f32_e32 v214, v214
	v_rcp_f32_e32 v215, v215
	v_rcp_f32_e32 v200, v200
	v_rcp_f32_e32 v201, v201
	v_rcp_f32_e32 v202, v202
	v_rcp_f32_e32 v203, v203
	s_nop 0
	v_mul_f32_e32 v108, v108, v212
	v_mul_f32_e32 v109, v109, v213
	v_mul_f32_e32 v110, v110, v214
	v_mul_f32_e32 v111, v111, v215
	v_mul_f32_e32 v104, v104, v200
	v_mul_f32_e32 v105, v105, v201
	v_mul_f32_e32 v106, v106, v202
	v_mul_f32_e32 v107, v107, v203
	v_cvt_pk_bf16_f32 v108, v108, v109
	v_cvt_pk_bf16_f32 v109, v110, v111
	v_cvt_pk_bf16_f32 v110, v104, v105
	v_cvt_pk_bf16_f32 v111, v106, v107
	global_store_dwordx4 v205, v[108:111], s[88:89]
	s_add_u32 s92, s92, 0x2c000
	s_addc_u32 s93, s93, 0
	s_add_u32 s100, s92, 0x1800
	s_addc_u32 s101, s93, 0
	global_load_dwordx4 v[152:155], v205, s[100:101]
	s_waitcnt vmcnt(14)
	v_lshlrev_b32_e32 v212, 16, v164
	v_and_b32_e32 v213, 0xffff0000, v164
	v_lshlrev_b32_e32 v214, 16, v165
	v_and_b32_e32 v215, 0xffff0000, v165
	v_lshlrev_b32_e32 v200, 16, v166
	v_and_b32_e32 v201, 0xffff0000, v166
	v_lshlrev_b32_e32 v202, 16, v167
	v_and_b32_e32 v203, 0xffff0000, v167
	v_mul_f32_e32 v212, 0xbfb8aa3b, v212
	v_mul_f32_e32 v213, 0xbfb8aa3b, v213
	v_mul_f32_e32 v214, 0xbfb8aa3b, v214
	v_mul_f32_e32 v215, 0xbfb8aa3b, v215
	v_mul_f32_e32 v200, 0xbfb8aa3b, v200
	v_mul_f32_e32 v201, 0xbfb8aa3b, v201
	v_mul_f32_e32 v202, 0xbfb8aa3b, v202
	v_mul_f32_e32 v203, 0xbfb8aa3b, v203
	v_exp_f32_e32 v212, v212
	v_exp_f32_e32 v213, v213
	v_exp_f32_e32 v214, v214
	v_exp_f32_e32 v215, v215
	v_exp_f32_e32 v200, v200
	v_exp_f32_e32 v201, v201
	v_exp_f32_e32 v202, v202
	v_exp_f32_e32 v203, v203
	s_nop 0
	v_add_f32_e32 v212, 1.0, v212
	v_add_f32_e32 v213, 1.0, v213
	v_add_f32_e32 v214, 1.0, v214
	v_add_f32_e32 v215, 1.0, v215
	v_add_f32_e32 v200, 1.0, v200
	v_add_f32_e32 v201, 1.0, v201
	v_add_f32_e32 v202, 1.0, v202
	v_add_f32_e32 v203, 1.0, v203
	v_rcp_f32_e32 v212, v212
	v_rcp_f32_e32 v213, v213
	v_rcp_f32_e32 v214, v214
	v_rcp_f32_e32 v215, v215
	v_rcp_f32_e32 v200, v200
	v_rcp_f32_e32 v201, v201
	v_rcp_f32_e32 v202, v202
	v_rcp_f32_e32 v203, v203
	s_nop 0
	v_mul_f32_e32 v100, v100, v212
	v_mul_f32_e32 v101, v101, v213
	v_mul_f32_e32 v102, v102, v214
	v_mul_f32_e32 v103, v103, v215
	v_mul_f32_e32 v96, v96, v200
	v_mul_f32_e32 v97, v97, v201
	v_mul_f32_e32 v98, v98, v202
	v_mul_f32_e32 v99, v99, v203
	v_cvt_pk_bf16_f32 v100, v100, v101
	v_cvt_pk_bf16_f32 v101, v102, v103
	v_cvt_pk_bf16_f32 v102, v96, v97
	v_cvt_pk_bf16_f32 v103, v98, v99
	global_store_dwordx4 v205, v[100:103], s[88:89] offset:256
	s_add_u32 s100, s92, 0x1800
	s_addc_u32 s101, s93, 0
	global_load_dwordx4 v[164:167], v205, s[100:101] offset:256
	s_add_u32 s88, s88, 0x2c000
	s_addc_u32 s89, s89, 0
	s_waitcnt vmcnt(15)
	v_lshlrev_b32_e32 v212, 16, v168
	v_and_b32_e32 v213, 0xffff0000, v168
	v_lshlrev_b32_e32 v214, 16, v169
	v_and_b32_e32 v215, 0xffff0000, v169
	v_lshlrev_b32_e32 v200, 16, v170
	v_and_b32_e32 v201, 0xffff0000, v170
	v_lshlrev_b32_e32 v202, 16, v171
	v_and_b32_e32 v203, 0xffff0000, v171
	v_mul_f32_e32 v212, 0xbfb8aa3b, v212
	v_mul_f32_e32 v213, 0xbfb8aa3b, v213
	v_mul_f32_e32 v214, 0xbfb8aa3b, v214
	v_mul_f32_e32 v215, 0xbfb8aa3b, v215
	v_mul_f32_e32 v200, 0xbfb8aa3b, v200
	v_mul_f32_e32 v201, 0xbfb8aa3b, v201
	v_mul_f32_e32 v202, 0xbfb8aa3b, v202
	v_mul_f32_e32 v203, 0xbfb8aa3b, v203
	v_exp_f32_e32 v212, v212
	v_exp_f32_e32 v213, v213
	v_exp_f32_e32 v214, v214
	v_exp_f32_e32 v215, v215
	v_exp_f32_e32 v200, v200
	v_exp_f32_e32 v201, v201
	v_exp_f32_e32 v202, v202
	v_exp_f32_e32 v203, v203
	s_nop 0
	v_add_f32_e32 v212, 1.0, v212
	v_add_f32_e32 v213, 1.0, v213
	v_add_f32_e32 v214, 1.0, v214
	v_add_f32_e32 v215, 1.0, v215
	v_add_f32_e32 v200, 1.0, v200
	v_add_f32_e32 v201, 1.0, v201
	v_add_f32_e32 v202, 1.0, v202
	v_add_f32_e32 v203, 1.0, v203
	v_rcp_f32_e32 v212, v212
	v_rcp_f32_e32 v213, v213
	v_rcp_f32_e32 v214, v214
	v_rcp_f32_e32 v215, v215
	v_rcp_f32_e32 v200, v200
	v_rcp_f32_e32 v201, v201
	v_rcp_f32_e32 v202, v202
	v_rcp_f32_e32 v203, v203
	s_nop 0
	v_mul_f32_e32 v92, v92, v212
	v_mul_f32_e32 v93, v93, v213
	v_mul_f32_e32 v94, v94, v214
	v_mul_f32_e32 v95, v95, v215
	v_mul_f32_e32 v88, v88, v200
	v_mul_f32_e32 v89, v89, v201
	v_mul_f32_e32 v90, v90, v202
	v_mul_f32_e32 v91, v91, v203
	v_cvt_pk_bf16_f32 v92, v92, v93
	v_cvt_pk_bf16_f32 v93, v94, v95
	v_cvt_pk_bf16_f32 v94, v88, v89
	v_cvt_pk_bf16_f32 v95, v90, v91
	global_store_dwordx4 v205, v[92:95], s[88:89]
	s_waitcnt vmcnt(15)
	v_lshlrev_b32_e32 v212, 16, v172
	v_and_b32_e32 v213, 0xffff0000, v172
	v_lshlrev_b32_e32 v214, 16, v173
	v_and_b32_e32 v215, 0xffff0000, v173
	v_lshlrev_b32_e32 v200, 16, v174
	v_and_b32_e32 v201, 0xffff0000, v174
	v_lshlrev_b32_e32 v202, 16, v175
	v_and_b32_e32 v203, 0xffff0000, v175
	v_mul_f32_e32 v212, 0xbfb8aa3b, v212
	v_mul_f32_e32 v213, 0xbfb8aa3b, v213
	v_mul_f32_e32 v214, 0xbfb8aa3b, v214
	v_mul_f32_e32 v215, 0xbfb8aa3b, v215
	v_mul_f32_e32 v200, 0xbfb8aa3b, v200
	v_mul_f32_e32 v201, 0xbfb8aa3b, v201
	v_mul_f32_e32 v202, 0xbfb8aa3b, v202
	v_mul_f32_e32 v203, 0xbfb8aa3b, v203
	v_exp_f32_e32 v212, v212
	v_exp_f32_e32 v213, v213
	v_exp_f32_e32 v214, v214
	v_exp_f32_e32 v215, v215
	v_exp_f32_e32 v200, v200
	v_exp_f32_e32 v201, v201
	v_exp_f32_e32 v202, v202
	v_exp_f32_e32 v203, v203
	s_nop 0
	v_add_f32_e32 v212, 1.0, v212
	v_add_f32_e32 v213, 1.0, v213
	v_add_f32_e32 v214, 1.0, v214
	v_add_f32_e32 v215, 1.0, v215
	v_add_f32_e32 v200, 1.0, v200
	v_add_f32_e32 v201, 1.0, v201
	v_add_f32_e32 v202, 1.0, v202
	v_add_f32_e32 v203, 1.0, v203
	v_rcp_f32_e32 v212, v212
	v_rcp_f32_e32 v213, v213
	v_rcp_f32_e32 v214, v214
	v_rcp_f32_e32 v215, v215
	v_rcp_f32_e32 v200, v200
	v_rcp_f32_e32 v201, v201
	v_rcp_f32_e32 v202, v202
	v_rcp_f32_e32 v203, v203
	s_nop 0
	v_mul_f32_e32 v84, v84, v212
	v_mul_f32_e32 v85, v85, v213
	v_mul_f32_e32 v86, v86, v214
	v_mul_f32_e32 v87, v87, v215
	v_mul_f32_e32 v80, v80, v200
	v_mul_f32_e32 v81, v81, v201
	v_mul_f32_e32 v82, v82, v202
	v_mul_f32_e32 v83, v83, v203
	v_cvt_pk_bf16_f32 v84, v84, v85
	v_cvt_pk_bf16_f32 v85, v86, v87
	v_cvt_pk_bf16_f32 v86, v80, v81
	v_cvt_pk_bf16_f32 v87, v82, v83
	global_store_dwordx4 v205, v[84:87], s[88:89] offset:256
	s_add_u32 s88, s88, 0x2c000
	s_addc_u32 s89, s89, 0
	s_waitcnt vmcnt(15)
	v_lshlrev_b32_e32 v212, 16, v176
	v_and_b32_e32 v213, 0xffff0000, v176
	v_lshlrev_b32_e32 v214, 16, v177
	v_and_b32_e32 v215, 0xffff0000, v177
	v_lshlrev_b32_e32 v200, 16, v178
	v_and_b32_e32 v201, 0xffff0000, v178
	v_lshlrev_b32_e32 v202, 16, v179
	v_and_b32_e32 v203, 0xffff0000, v179
	v_mul_f32_e32 v212, 0xbfb8aa3b, v212
	v_mul_f32_e32 v213, 0xbfb8aa3b, v213
	v_mul_f32_e32 v214, 0xbfb8aa3b, v214
	v_mul_f32_e32 v215, 0xbfb8aa3b, v215
	v_mul_f32_e32 v200, 0xbfb8aa3b, v200
	v_mul_f32_e32 v201, 0xbfb8aa3b, v201
	v_mul_f32_e32 v202, 0xbfb8aa3b, v202
	v_mul_f32_e32 v203, 0xbfb8aa3b, v203
	v_exp_f32_e32 v212, v212
	v_exp_f32_e32 v213, v213
	v_exp_f32_e32 v214, v214
	v_exp_f32_e32 v215, v215
	v_exp_f32_e32 v200, v200
	v_exp_f32_e32 v201, v201
	v_exp_f32_e32 v202, v202
	v_exp_f32_e32 v203, v203
	s_nop 0
	v_add_f32_e32 v212, 1.0, v212
	v_add_f32_e32 v213, 1.0, v213
	v_add_f32_e32 v214, 1.0, v214
	v_add_f32_e32 v215, 1.0, v215
	v_add_f32_e32 v200, 1.0, v200
	v_add_f32_e32 v201, 1.0, v201
	v_add_f32_e32 v202, 1.0, v202
	v_add_f32_e32 v203, 1.0, v203
	v_rcp_f32_e32 v212, v212
	v_rcp_f32_e32 v213, v213
	v_rcp_f32_e32 v214, v214
	v_rcp_f32_e32 v215, v215
	v_rcp_f32_e32 v200, v200
	v_rcp_f32_e32 v201, v201
	v_rcp_f32_e32 v202, v202
	v_rcp_f32_e32 v203, v203
	s_nop 0
	v_mul_f32_e32 v76, v76, v212
	v_mul_f32_e32 v77, v77, v213
	v_mul_f32_e32 v78, v78, v214
	v_mul_f32_e32 v79, v79, v215
	v_mul_f32_e32 v72, v72, v200
	v_mul_f32_e32 v73, v73, v201
	v_mul_f32_e32 v74, v74, v202
	v_mul_f32_e32 v75, v75, v203
	v_cvt_pk_bf16_f32 v76, v76, v77
	v_cvt_pk_bf16_f32 v77, v78, v79
	v_cvt_pk_bf16_f32 v78, v72, v73
	v_cvt_pk_bf16_f32 v79, v74, v75
	global_store_dwordx4 v205, v[76:79], s[88:89]
	s_waitcnt vmcnt(15)
	v_lshlrev_b32_e32 v212, 16, v180
	v_and_b32_e32 v213, 0xffff0000, v180
	v_lshlrev_b32_e32 v214, 16, v181
	v_and_b32_e32 v215, 0xffff0000, v181
	v_lshlrev_b32_e32 v200, 16, v182
	v_and_b32_e32 v201, 0xffff0000, v182
	v_lshlrev_b32_e32 v202, 16, v183
	v_and_b32_e32 v203, 0xffff0000, v183
	v_mul_f32_e32 v212, 0xbfb8aa3b, v212
	v_mul_f32_e32 v213, 0xbfb8aa3b, v213
	v_mul_f32_e32 v214, 0xbfb8aa3b, v214
	v_mul_f32_e32 v215, 0xbfb8aa3b, v215
	v_mul_f32_e32 v200, 0xbfb8aa3b, v200
	v_mul_f32_e32 v201, 0xbfb8aa3b, v201
	v_mul_f32_e32 v202, 0xbfb8aa3b, v202
	v_mul_f32_e32 v203, 0xbfb8aa3b, v203
	v_exp_f32_e32 v212, v212
	v_exp_f32_e32 v213, v213
	v_exp_f32_e32 v214, v214
	v_exp_f32_e32 v215, v215
	v_exp_f32_e32 v200, v200
	v_exp_f32_e32 v201, v201
	v_exp_f32_e32 v202, v202
	v_exp_f32_e32 v203, v203
	s_nop 0
	v_add_f32_e32 v212, 1.0, v212
	v_add_f32_e32 v213, 1.0, v213
	v_add_f32_e32 v214, 1.0, v214
	v_add_f32_e32 v215, 1.0, v215
	v_add_f32_e32 v200, 1.0, v200
	v_add_f32_e32 v201, 1.0, v201
	v_add_f32_e32 v202, 1.0, v202
	v_add_f32_e32 v203, 1.0, v203
	v_rcp_f32_e32 v212, v212
	v_rcp_f32_e32 v213, v213
	v_rcp_f32_e32 v214, v214
	v_rcp_f32_e32 v215, v215
	v_rcp_f32_e32 v200, v200
	v_rcp_f32_e32 v201, v201
	v_rcp_f32_e32 v202, v202
	v_rcp_f32_e32 v203, v203
	s_nop 0
	v_mul_f32_e32 v68, v68, v212
	v_mul_f32_e32 v69, v69, v213
	v_mul_f32_e32 v70, v70, v214
	v_mul_f32_e32 v71, v71, v215
	v_mul_f32_e32 v64, v64, v200
	v_mul_f32_e32 v65, v65, v201
	v_mul_f32_e32 v66, v66, v202
	v_mul_f32_e32 v67, v67, v203
	v_cvt_pk_bf16_f32 v68, v68, v69
	v_cvt_pk_bf16_f32 v69, v70, v71
	v_cvt_pk_bf16_f32 v70, v64, v65
	v_cvt_pk_bf16_f32 v71, v66, v67
	global_store_dwordx4 v205, v[68:71], s[88:89] offset:256
	s_add_u32 s88, s88, 0xdc000
	s_addc_u32 s89, s89, 0
	s_waitcnt vmcnt(15)
	v_lshlrev_b32_e32 v212, 16, v184
	v_and_b32_e32 v213, 0xffff0000, v184
	v_lshlrev_b32_e32 v214, 16, v185
	v_and_b32_e32 v215, 0xffff0000, v185
	v_lshlrev_b32_e32 v200, 16, v186
	v_and_b32_e32 v201, 0xffff0000, v186
	v_lshlrev_b32_e32 v202, 16, v187
	v_and_b32_e32 v203, 0xffff0000, v187
	v_mul_f32_e32 v212, 0xbfb8aa3b, v212
	v_mul_f32_e32 v213, 0xbfb8aa3b, v213
	v_mul_f32_e32 v214, 0xbfb8aa3b, v214
	v_mul_f32_e32 v215, 0xbfb8aa3b, v215
	v_mul_f32_e32 v200, 0xbfb8aa3b, v200
	v_mul_f32_e32 v201, 0xbfb8aa3b, v201
	v_mul_f32_e32 v202, 0xbfb8aa3b, v202
	v_mul_f32_e32 v203, 0xbfb8aa3b, v203
	v_exp_f32_e32 v212, v212
	v_exp_f32_e32 v213, v213
	v_exp_f32_e32 v214, v214
	v_exp_f32_e32 v215, v215
	v_exp_f32_e32 v200, v200
	v_exp_f32_e32 v201, v201
	v_exp_f32_e32 v202, v202
	v_exp_f32_e32 v203, v203
	s_nop 0
	v_add_f32_e32 v212, 1.0, v212
	v_add_f32_e32 v213, 1.0, v213
	v_add_f32_e32 v214, 1.0, v214
	v_add_f32_e32 v215, 1.0, v215
	v_add_f32_e32 v200, 1.0, v200
	v_add_f32_e32 v201, 1.0, v201
	v_add_f32_e32 v202, 1.0, v202
	v_add_f32_e32 v203, 1.0, v203
	v_rcp_f32_e32 v212, v212
	v_rcp_f32_e32 v213, v213
	v_rcp_f32_e32 v214, v214
	v_rcp_f32_e32 v215, v215
	v_rcp_f32_e32 v200, v200
	v_rcp_f32_e32 v201, v201
	v_rcp_f32_e32 v202, v202
	v_rcp_f32_e32 v203, v203
	s_nop 0
	v_mul_f32_e32 v60, v60, v212
	v_mul_f32_e32 v61, v61, v213
	v_mul_f32_e32 v62, v62, v214
	v_mul_f32_e32 v63, v63, v215
	v_mul_f32_e32 v56, v56, v200
	v_mul_f32_e32 v57, v57, v201
	v_mul_f32_e32 v58, v58, v202
	v_mul_f32_e32 v59, v59, v203
	v_cvt_pk_bf16_f32 v60, v60, v61
	v_cvt_pk_bf16_f32 v61, v62, v63
	v_cvt_pk_bf16_f32 v62, v56, v57
	v_cvt_pk_bf16_f32 v63, v58, v59
	global_store_dwordx4 v205, v[60:63], s[88:89]
	s_waitcnt vmcnt(15)
	v_lshlrev_b32_e32 v212, 16, v188
	v_and_b32_e32 v213, 0xffff0000, v188
	v_lshlrev_b32_e32 v214, 16, v189
	v_and_b32_e32 v215, 0xffff0000, v189
	v_lshlrev_b32_e32 v200, 16, v190
	v_and_b32_e32 v201, 0xffff0000, v190
	v_lshlrev_b32_e32 v202, 16, v191
	v_and_b32_e32 v203, 0xffff0000, v191
	v_mul_f32_e32 v212, 0xbfb8aa3b, v212
	v_mul_f32_e32 v213, 0xbfb8aa3b, v213
	v_mul_f32_e32 v214, 0xbfb8aa3b, v214
	v_mul_f32_e32 v215, 0xbfb8aa3b, v215
	v_mul_f32_e32 v200, 0xbfb8aa3b, v200
	v_mul_f32_e32 v201, 0xbfb8aa3b, v201
	v_mul_f32_e32 v202, 0xbfb8aa3b, v202
	v_mul_f32_e32 v203, 0xbfb8aa3b, v203
	v_exp_f32_e32 v212, v212
	v_exp_f32_e32 v213, v213
	v_exp_f32_e32 v214, v214
	v_exp_f32_e32 v215, v215
	v_exp_f32_e32 v200, v200
	v_exp_f32_e32 v201, v201
	v_exp_f32_e32 v202, v202
	v_exp_f32_e32 v203, v203
	s_nop 0
	v_add_f32_e32 v212, 1.0, v212
	v_add_f32_e32 v213, 1.0, v213
	v_add_f32_e32 v214, 1.0, v214
	v_add_f32_e32 v215, 1.0, v215
	v_add_f32_e32 v200, 1.0, v200
	v_add_f32_e32 v201, 1.0, v201
	v_add_f32_e32 v202, 1.0, v202
	v_add_f32_e32 v203, 1.0, v203
	v_rcp_f32_e32 v212, v212
	v_rcp_f32_e32 v213, v213
	v_rcp_f32_e32 v214, v214
	v_rcp_f32_e32 v215, v215
	v_rcp_f32_e32 v200, v200
	v_rcp_f32_e32 v201, v201
	v_rcp_f32_e32 v202, v202
	v_rcp_f32_e32 v203, v203
	s_nop 0
	v_mul_f32_e32 v52, v52, v212
	v_mul_f32_e32 v53, v53, v213
	v_mul_f32_e32 v54, v54, v214
	v_mul_f32_e32 v55, v55, v215
	v_mul_f32_e32 v48, v48, v200
	v_mul_f32_e32 v49, v49, v201
	v_mul_f32_e32 v50, v50, v202
	v_mul_f32_e32 v51, v51, v203
	v_cvt_pk_bf16_f32 v52, v52, v53
	v_cvt_pk_bf16_f32 v53, v54, v55
	v_cvt_pk_bf16_f32 v54, v48, v49
	v_cvt_pk_bf16_f32 v55, v50, v51
	global_store_dwordx4 v205, v[52:55], s[88:89] offset:256
	s_add_u32 s88, s88, 0x2c000
	s_addc_u32 s89, s89, 0
	s_waitcnt vmcnt(15)
	v_lshlrev_b32_e32 v212, 16, v192
	v_and_b32_e32 v213, 0xffff0000, v192
	v_lshlrev_b32_e32 v214, 16, v193
	v_and_b32_e32 v215, 0xffff0000, v193
	v_lshlrev_b32_e32 v200, 16, v194
	v_and_b32_e32 v201, 0xffff0000, v194
	v_lshlrev_b32_e32 v202, 16, v195
	v_and_b32_e32 v203, 0xffff0000, v195
	v_mul_f32_e32 v212, 0xbfb8aa3b, v212
	v_mul_f32_e32 v213, 0xbfb8aa3b, v213
	v_mul_f32_e32 v214, 0xbfb8aa3b, v214
	v_mul_f32_e32 v215, 0xbfb8aa3b, v215
	v_mul_f32_e32 v200, 0xbfb8aa3b, v200
	v_mul_f32_e32 v201, 0xbfb8aa3b, v201
	v_mul_f32_e32 v202, 0xbfb8aa3b, v202
	v_mul_f32_e32 v203, 0xbfb8aa3b, v203
	v_exp_f32_e32 v212, v212
	v_exp_f32_e32 v213, v213
	v_exp_f32_e32 v214, v214
	v_exp_f32_e32 v215, v215
	v_exp_f32_e32 v200, v200
	v_exp_f32_e32 v201, v201
	v_exp_f32_e32 v202, v202
	v_exp_f32_e32 v203, v203
	s_nop 0
	v_add_f32_e32 v212, 1.0, v212
	v_add_f32_e32 v213, 1.0, v213
	v_add_f32_e32 v214, 1.0, v214
	v_add_f32_e32 v215, 1.0, v215
	v_add_f32_e32 v200, 1.0, v200
	v_add_f32_e32 v201, 1.0, v201
	v_add_f32_e32 v202, 1.0, v202
	v_add_f32_e32 v203, 1.0, v203
	v_rcp_f32_e32 v212, v212
	v_rcp_f32_e32 v213, v213
	v_rcp_f32_e32 v214, v214
	v_rcp_f32_e32 v215, v215
	v_rcp_f32_e32 v200, v200
	v_rcp_f32_e32 v201, v201
	v_rcp_f32_e32 v202, v202
	v_rcp_f32_e32 v203, v203
	s_nop 0
	v_mul_f32_e32 v44, v44, v212
	v_mul_f32_e32 v45, v45, v213
	v_mul_f32_e32 v46, v46, v214
	v_mul_f32_e32 v47, v47, v215
	v_mul_f32_e32 v40, v40, v200
	v_mul_f32_e32 v41, v41, v201
	v_mul_f32_e32 v42, v42, v202
	v_mul_f32_e32 v43, v43, v203
	v_cvt_pk_bf16_f32 v44, v44, v45
	v_cvt_pk_bf16_f32 v45, v46, v47
	v_cvt_pk_bf16_f32 v46, v40, v41
	v_cvt_pk_bf16_f32 v47, v42, v43
	global_store_dwordx4 v205, v[44:47], s[88:89]
	s_waitcnt vmcnt(15)
	v_lshlrev_b32_e32 v212, 16, v196
	v_and_b32_e32 v213, 0xffff0000, v196
	v_lshlrev_b32_e32 v214, 16, v197
	v_and_b32_e32 v215, 0xffff0000, v197
	v_lshlrev_b32_e32 v200, 16, v198
	v_and_b32_e32 v201, 0xffff0000, v198
	v_lshlrev_b32_e32 v202, 16, v199
	v_and_b32_e32 v203, 0xffff0000, v199
	v_mul_f32_e32 v212, 0xbfb8aa3b, v212
	v_mul_f32_e32 v213, 0xbfb8aa3b, v213
	v_mul_f32_e32 v214, 0xbfb8aa3b, v214
	v_mul_f32_e32 v215, 0xbfb8aa3b, v215
	v_mul_f32_e32 v200, 0xbfb8aa3b, v200
	v_mul_f32_e32 v201, 0xbfb8aa3b, v201
	v_mul_f32_e32 v202, 0xbfb8aa3b, v202
	v_mul_f32_e32 v203, 0xbfb8aa3b, v203
	v_exp_f32_e32 v212, v212
	v_exp_f32_e32 v213, v213
	v_exp_f32_e32 v214, v214
	v_exp_f32_e32 v215, v215
	v_exp_f32_e32 v200, v200
	v_exp_f32_e32 v201, v201
	v_exp_f32_e32 v202, v202
	v_exp_f32_e32 v203, v203
	s_nop 0
	v_add_f32_e32 v212, 1.0, v212
	v_add_f32_e32 v213, 1.0, v213
	v_add_f32_e32 v214, 1.0, v214
	v_add_f32_e32 v215, 1.0, v215
	v_add_f32_e32 v200, 1.0, v200
	v_add_f32_e32 v201, 1.0, v201
	v_add_f32_e32 v202, 1.0, v202
	v_add_f32_e32 v203, 1.0, v203
	v_rcp_f32_e32 v212, v212
	v_rcp_f32_e32 v213, v213
	v_rcp_f32_e32 v214, v214
	v_rcp_f32_e32 v215, v215
	v_rcp_f32_e32 v200, v200
	v_rcp_f32_e32 v201, v201
	v_rcp_f32_e32 v202, v202
	v_rcp_f32_e32 v203, v203
	s_nop 0
	v_mul_f32_e32 v36, v36, v212
	v_mul_f32_e32 v37, v37, v213
	v_mul_f32_e32 v38, v38, v214
	v_mul_f32_e32 v39, v39, v215
	v_mul_f32_e32 v32, v32, v200
	v_mul_f32_e32 v33, v33, v201
	v_mul_f32_e32 v34, v34, v202
	v_mul_f32_e32 v35, v35, v203
	v_cvt_pk_bf16_f32 v36, v36, v37
	v_cvt_pk_bf16_f32 v37, v38, v39
	v_cvt_pk_bf16_f32 v38, v32, v33
	v_cvt_pk_bf16_f32 v39, v34, v35
	global_store_dwordx4 v205, v[36:39], s[88:89] offset:256
	s_add_u32 s88, s88, 0x2c000
	s_addc_u32 s89, s89, 0
	s_waitcnt vmcnt(14)
	v_lshlrev_b32_e32 v212, 16, v128
	v_and_b32_e32 v213, 0xffff0000, v128
	v_lshlrev_b32_e32 v214, 16, v129
	v_and_b32_e32 v215, 0xffff0000, v129
	v_lshlrev_b32_e32 v200, 16, v130
	v_and_b32_e32 v201, 0xffff0000, v130
	v_lshlrev_b32_e32 v202, 16, v131
	v_and_b32_e32 v203, 0xffff0000, v131
	v_mul_f32_e32 v212, 0xbfb8aa3b, v212
	v_mul_f32_e32 v213, 0xbfb8aa3b, v213
	v_mul_f32_e32 v214, 0xbfb8aa3b, v214
	v_mul_f32_e32 v215, 0xbfb8aa3b, v215
	v_mul_f32_e32 v200, 0xbfb8aa3b, v200
	v_mul_f32_e32 v201, 0xbfb8aa3b, v201
	v_mul_f32_e32 v202, 0xbfb8aa3b, v202
	v_mul_f32_e32 v203, 0xbfb8aa3b, v203
	v_exp_f32_e32 v212, v212
	v_exp_f32_e32 v213, v213
	v_exp_f32_e32 v214, v214
	v_exp_f32_e32 v215, v215
	v_exp_f32_e32 v200, v200
	v_exp_f32_e32 v201, v201
	v_exp_f32_e32 v202, v202
	v_exp_f32_e32 v203, v203
	s_nop 0
	v_add_f32_e32 v212, 1.0, v212
	v_add_f32_e32 v213, 1.0, v213
	v_add_f32_e32 v214, 1.0, v214
	v_add_f32_e32 v215, 1.0, v215
	v_add_f32_e32 v200, 1.0, v200
	v_add_f32_e32 v201, 1.0, v201
	v_add_f32_e32 v202, 1.0, v202
	v_add_f32_e32 v203, 1.0, v203
	v_rcp_f32_e32 v212, v212
	v_rcp_f32_e32 v213, v213
	v_rcp_f32_e32 v214, v214
	v_rcp_f32_e32 v215, v215
	v_rcp_f32_e32 v200, v200
	v_rcp_f32_e32 v201, v201
	v_rcp_f32_e32 v202, v202
	v_rcp_f32_e32 v203, v203
	s_nop 0
	v_mul_f32_e32 v28, v28, v212
	v_mul_f32_e32 v29, v29, v213
	v_mul_f32_e32 v30, v30, v214
	v_mul_f32_e32 v31, v31, v215
	v_mul_f32_e32 v24, v24, v200
	v_mul_f32_e32 v25, v25, v201
	v_mul_f32_e32 v26, v26, v202
	v_mul_f32_e32 v27, v27, v203
	v_cvt_pk_bf16_f32 v28, v28, v29
	v_cvt_pk_bf16_f32 v29, v30, v31
	v_cvt_pk_bf16_f32 v30, v24, v25
	v_cvt_pk_bf16_f32 v31, v26, v27
	global_store_dwordx4 v205, v[28:31], s[88:89]
	s_waitcnt vmcnt(13)
	v_lshlrev_b32_e32 v212, 16, v148
	v_and_b32_e32 v213, 0xffff0000, v148
	v_lshlrev_b32_e32 v214, 16, v149
	v_and_b32_e32 v215, 0xffff0000, v149
	v_lshlrev_b32_e32 v200, 16, v150
	v_and_b32_e32 v201, 0xffff0000, v150
	v_lshlrev_b32_e32 v202, 16, v151
	v_and_b32_e32 v203, 0xffff0000, v151
	v_mul_f32_e32 v212, 0xbfb8aa3b, v212
	v_mul_f32_e32 v213, 0xbfb8aa3b, v213
	v_mul_f32_e32 v214, 0xbfb8aa3b, v214
	v_mul_f32_e32 v215, 0xbfb8aa3b, v215
	v_mul_f32_e32 v200, 0xbfb8aa3b, v200
	v_mul_f32_e32 v201, 0xbfb8aa3b, v201
	v_mul_f32_e32 v202, 0xbfb8aa3b, v202
	v_mul_f32_e32 v203, 0xbfb8aa3b, v203
	v_exp_f32_e32 v212, v212
	v_exp_f32_e32 v213, v213
	v_exp_f32_e32 v214, v214
	v_exp_f32_e32 v215, v215
	v_exp_f32_e32 v200, v200
	v_exp_f32_e32 v201, v201
	v_exp_f32_e32 v202, v202
	v_exp_f32_e32 v203, v203
	s_nop 0
	v_add_f32_e32 v212, 1.0, v212
	v_add_f32_e32 v213, 1.0, v213
	v_add_f32_e32 v214, 1.0, v214
	v_add_f32_e32 v215, 1.0, v215
	v_add_f32_e32 v200, 1.0, v200
	v_add_f32_e32 v201, 1.0, v201
	v_add_f32_e32 v202, 1.0, v202
	v_add_f32_e32 v203, 1.0, v203
	v_rcp_f32_e32 v212, v212
	v_rcp_f32_e32 v213, v213
	v_rcp_f32_e32 v214, v214
	v_rcp_f32_e32 v215, v215
	v_rcp_f32_e32 v200, v200
	v_rcp_f32_e32 v201, v201
	v_rcp_f32_e32 v202, v202
	v_rcp_f32_e32 v203, v203
	s_nop 0
	v_mul_f32_e32 v20, v20, v212
	v_mul_f32_e32 v21, v21, v213
	v_mul_f32_e32 v22, v22, v214
	v_mul_f32_e32 v23, v23, v215
	v_mul_f32_e32 v16, v16, v200
	v_mul_f32_e32 v17, v17, v201
	v_mul_f32_e32 v18, v18, v202
	v_mul_f32_e32 v19, v19, v203
	v_cvt_pk_bf16_f32 v20, v20, v21
	v_cvt_pk_bf16_f32 v21, v22, v23
	v_cvt_pk_bf16_f32 v22, v16, v17
	v_cvt_pk_bf16_f32 v23, v18, v19
	global_store_dwordx4 v205, v[20:23], s[88:89] offset:256
	s_add_u32 s88, s88, 0x2c000
	s_addc_u32 s89, s89, 0
	s_waitcnt vmcnt(12)
	v_lshlrev_b32_e32 v212, 16, v152
	v_and_b32_e32 v213, 0xffff0000, v152
	v_lshlrev_b32_e32 v214, 16, v153
	v_and_b32_e32 v215, 0xffff0000, v153
	v_lshlrev_b32_e32 v200, 16, v154
	v_and_b32_e32 v201, 0xffff0000, v154
	v_lshlrev_b32_e32 v202, 16, v155
	v_and_b32_e32 v203, 0xffff0000, v155
	v_mul_f32_e32 v212, 0xbfb8aa3b, v212
	v_mul_f32_e32 v213, 0xbfb8aa3b, v213
	v_mul_f32_e32 v214, 0xbfb8aa3b, v214
	v_mul_f32_e32 v215, 0xbfb8aa3b, v215
	v_mul_f32_e32 v200, 0xbfb8aa3b, v200
	v_mul_f32_e32 v201, 0xbfb8aa3b, v201
	v_mul_f32_e32 v202, 0xbfb8aa3b, v202
	v_mul_f32_e32 v203, 0xbfb8aa3b, v203
	v_exp_f32_e32 v212, v212
	v_exp_f32_e32 v213, v213
	v_exp_f32_e32 v214, v214
	v_exp_f32_e32 v215, v215
	v_exp_f32_e32 v200, v200
	v_exp_f32_e32 v201, v201
	v_exp_f32_e32 v202, v202
	v_exp_f32_e32 v203, v203
	s_nop 0
	v_add_f32_e32 v212, 1.0, v212
	v_add_f32_e32 v213, 1.0, v213
	v_add_f32_e32 v214, 1.0, v214
	v_add_f32_e32 v215, 1.0, v215
	v_add_f32_e32 v200, 1.0, v200
	v_add_f32_e32 v201, 1.0, v201
	v_add_f32_e32 v202, 1.0, v202
	v_add_f32_e32 v203, 1.0, v203
	v_rcp_f32_e32 v212, v212
	v_rcp_f32_e32 v213, v213
	v_rcp_f32_e32 v214, v214
	v_rcp_f32_e32 v215, v215
	v_rcp_f32_e32 v200, v200
	v_rcp_f32_e32 v201, v201
	v_rcp_f32_e32 v202, v202
	v_rcp_f32_e32 v203, v203
	s_nop 0
	v_mul_f32_e32 v12, v12, v212
	v_mul_f32_e32 v13, v13, v213
	v_mul_f32_e32 v14, v14, v214
	v_mul_f32_e32 v15, v15, v215
	v_mul_f32_e32 v8, v8, v200
	v_mul_f32_e32 v9, v9, v201
	v_mul_f32_e32 v10, v10, v202
	v_mul_f32_e32 v11, v11, v203
	v_cvt_pk_bf16_f32 v12, v12, v13
	v_cvt_pk_bf16_f32 v13, v14, v15
	v_cvt_pk_bf16_f32 v14, v8, v9
	v_cvt_pk_bf16_f32 v15, v10, v11
	global_store_dwordx4 v205, v[12:15], s[88:89]
	s_waitcnt vmcnt(11)
	v_lshlrev_b32_e32 v212, 16, v164
	v_and_b32_e32 v213, 0xffff0000, v164
	v_lshlrev_b32_e32 v214, 16, v165
	v_and_b32_e32 v215, 0xffff0000, v165
	v_lshlrev_b32_e32 v200, 16, v166
	v_and_b32_e32 v201, 0xffff0000, v166
	v_lshlrev_b32_e32 v202, 16, v167
	v_and_b32_e32 v203, 0xffff0000, v167
	v_mul_f32_e32 v212, 0xbfb8aa3b, v212
	v_mul_f32_e32 v213, 0xbfb8aa3b, v213
	v_mul_f32_e32 v214, 0xbfb8aa3b, v214
	v_mul_f32_e32 v215, 0xbfb8aa3b, v215
	v_mul_f32_e32 v200, 0xbfb8aa3b, v200
	v_mul_f32_e32 v201, 0xbfb8aa3b, v201
	v_mul_f32_e32 v202, 0xbfb8aa3b, v202
	v_mul_f32_e32 v203, 0xbfb8aa3b, v203
	v_exp_f32_e32 v212, v212
	v_exp_f32_e32 v213, v213
	v_exp_f32_e32 v214, v214
	v_exp_f32_e32 v215, v215
	v_exp_f32_e32 v200, v200
	v_exp_f32_e32 v201, v201
	v_exp_f32_e32 v202, v202
	v_exp_f32_e32 v203, v203
	s_nop 0
	v_add_f32_e32 v212, 1.0, v212
	v_add_f32_e32 v213, 1.0, v213
	v_add_f32_e32 v214, 1.0, v214
	v_add_f32_e32 v215, 1.0, v215
	v_add_f32_e32 v200, 1.0, v200
	v_add_f32_e32 v201, 1.0, v201
	v_add_f32_e32 v202, 1.0, v202
	v_add_f32_e32 v203, 1.0, v203
	v_rcp_f32_e32 v212, v212
	v_rcp_f32_e32 v213, v213
	v_rcp_f32_e32 v214, v214
	v_rcp_f32_e32 v215, v215
	v_rcp_f32_e32 v200, v200
	v_rcp_f32_e32 v201, v201
	v_rcp_f32_e32 v202, v202
	v_rcp_f32_e32 v203, v203
	s_nop 0
	v_mul_f32_e32 v4, v4, v212
	v_mul_f32_e32 v5, v5, v213
	v_mul_f32_e32 v6, v6, v214
	v_mul_f32_e32 v7, v7, v215
	v_mul_f32_e32 v0, v0, v200
	v_mul_f32_e32 v1, v1, v201
	v_mul_f32_e32 v2, v2, v202
	v_mul_f32_e32 v3, v3, v203
	v_cvt_pk_bf16_f32 v4, v4, v5
	v_cvt_pk_bf16_f32 v5, v6, v7
	v_cvt_pk_bf16_f32 v6, v0, v1
	v_cvt_pk_bf16_f32 v7, v2, v3
	global_store_dwordx4 v205, v[4:7], s[88:89] offset:256
	s_and_b64 vcc, exec, s[10:11]
	s_mov_b64 s[10:11], -1
	s_cbranch_vccnz .LBB0_891
	s_andn2_b64 vcc, exec, s[14:15]
	s_cbranch_vccnz .LBB0_890
	s_barrier
	s_branch .LBB0_890

.LBB0_930:
	v_lshrrev_b32_e32 v162, 6, v206
	v_and_b32_e32 v204, 63, v206
	v_lshrrev_b32_e32 v163, 2, v162
	v_and_b32_e32 v162, 3, v162
	v_lshlrev_b32_e32 v163, 6, v163
	v_lshrrev_b32_e32 v210, 4, v204
	v_and_b32_e32 v211, 15, v204
	v_add_u32_e32 v163, v163, v211
	s_lshl_b32 vcc_lo, s65, 8
	v_add_u32_e32 v163, vcc_lo, v163
	v_lshlrev_b32_e32 v204, 5, v162
	v_lshl_add_u32 v204, v210, 3, v204
	s_lshl_b32 vcc_lo, s66, 8
	v_add_u32_e32 v204, vcc_lo, v204
	v_mov_b32_e32 v205, 0x2c00
	v_mul_u32_u24_e32 v205, v163, v205
	v_lshl_add_u32 v205, v204, 1, v205
	s_add_u32 s88, s96, 0x11f00400
	s_addc_u32 s89, s97, 0
	s_add_u32 s92, s96, 0x11f00400
	s_addc_u32 s93, s97, 0
	s_add_u32 s100, s92, 0x2000
	s_addc_u32 s101, s93, 0
	global_load_dwordx4 v[128:131], v205, s[100:101]
	global_load_dwordx4 v[148:151], v205, s[92:93]
	s_add_u32 s100, s92, 0x2000
	s_addc_u32 s101, s93, 0
	global_load_dwordx4 v[152:155], v205, s[100:101] offset:256
	global_load_dwordx4 v[164:167], v205, s[92:93] offset:256
	s_add_u32 s92, s92, 0x2c000
	s_addc_u32 s93, s93, 0
	s_add_u32 s100, s92, 0x2000
	s_addc_u32 s101, s93, 0
	global_load_dwordx4 v[168:171], v205, s[100:101]
	global_load_dwordx4 v[172:175], v205, s[92:93]
	s_add_u32 s100, s92, 0x2000
	s_addc_u32 s101, s93, 0
	global_load_dwordx4 v[176:179], v205, s[100:101] offset:256
	global_load_dwordx4 v[180:183], v205, s[92:93] offset:256
	s_add_u32 s92, s92, 0x2c000
	s_addc_u32 s93, s93, 0
	s_add_u32 s100, s92, 0x2000
	s_addc_u32 s101, s93, 0
	global_load_dwordx4 v[184:187], v205, s[100:101]
	global_load_dwordx4 v[188:191], v205, s[92:93]
	s_add_u32 s100, s92, 0x2000
	s_addc_u32 s101, s93, 0
	global_load_dwordx4 v[192:195], v205, s[100:101] offset:256
	global_load_dwordx4 v[196:199], v205, s[92:93] offset:256
	s_waitcnt vmcnt(10)
	v_lshlrev_b32_e32 v212, 16, v128
	v_and_b32_e32 v213, 0xffff0000, v128
	v_lshlrev_b32_e32 v214, 16, v129
	v_and_b32_e32 v215, 0xffff0000, v129
	v_lshlrev_b32_e32 v200, 16, v130
	v_and_b32_e32 v201, 0xffff0000, v130
	v_lshlrev_b32_e32 v202, 16, v131
	v_and_b32_e32 v203, 0xffff0000, v131
	v_mul_f32_e32 v212, 0xbfb8aa3b, v212
	v_mul_f32_e32 v213, 0xbfb8aa3b, v213
	v_mul_f32_e32 v214, 0xbfb8aa3b, v214
	v_mul_f32_e32 v215, 0xbfb8aa3b, v215
	v_mul_f32_e32 v200, 0xbfb8aa3b, v200
	v_mul_f32_e32 v201, 0xbfb8aa3b, v201
	v_mul_f32_e32 v202, 0xbfb8aa3b, v202
	v_mul_f32_e32 v203, 0xbfb8aa3b, v203
	v_exp_f32_e32 v212, v212
	v_exp_f32_e32 v213, v213
	v_exp_f32_e32 v214, v214
	v_exp_f32_e32 v215, v215
	v_exp_f32_e32 v200, v200
	v_exp_f32_e32 v201, v201
	v_exp_f32_e32 v202, v202
	v_exp_f32_e32 v203, v203
	s_nop 0
	v_add_f32_e32 v212, 1.0, v212
	v_add_f32_e32 v213, 1.0, v213
	v_add_f32_e32 v214, 1.0, v214
	v_add_f32_e32 v215, 1.0, v215
	v_add_f32_e32 v200, 1.0, v200
	v_add_f32_e32 v201, 1.0, v201
	v_add_f32_e32 v202, 1.0, v202
	v_add_f32_e32 v203, 1.0, v203
	v_rcp_f32_e32 v212, v212
	v_rcp_f32_e32 v213, v213
	v_rcp_f32_e32 v214, v214
	v_rcp_f32_e32 v215, v215
	v_rcp_f32_e32 v200, v200
	v_rcp_f32_e32 v201, v201
	v_rcp_f32_e32 v202, v202
	v_rcp_f32_e32 v203, v203
	s_nop 0
	v_mul_f32_e32 v124, v124, v212
	v_mul_f32_e32 v125, v125, v213
	v_mul_f32_e32 v126, v126, v214
	v_mul_f32_e32 v127, v127, v215
	v_mul_f32_e32 v120, v120, v200
	v_mul_f32_e32 v121, v121, v201
	v_mul_f32_e32 v122, v122, v202
	v_mul_f32_e32 v123, v123, v203
	v_lshlrev_b32_e32 v212, 16, v148
	v_and_b32_e32 v213, 0xffff0000, v148
	v_lshlrev_b32_e32 v214, 16, v149
	v_and_b32_e32 v215, 0xffff0000, v149
	v_lshlrev_b32_e32 v200, 16, v150
	v_and_b32_e32 v201, 0xffff0000, v150
	v_lshlrev_b32_e32 v202, 16, v151
	v_and_b32_e32 v203, 0xffff0000, v151
	v_add_f32_e32 v124, v124, v212
	v_add_f32_e32 v125, v125, v213
	v_add_f32_e32 v126, v126, v214
	v_add_f32_e32 v127, v127, v215
	v_add_f32_e32 v120, v120, v200
	v_add_f32_e32 v121, v121, v201
	v_add_f32_e32 v122, v122, v202
	v_add_f32_e32 v123, v123, v203
	v_cvt_pk_bf16_f32 v124, v124, v125
	v_cvt_pk_bf16_f32 v125, v126, v127
	v_cvt_pk_bf16_f32 v126, v120, v121
	v_cvt_pk_bf16_f32 v127, v122, v123
	global_store_dwordx4 v205, v[124:127], s[88:89]
	s_add_u32 s92, s92, 0x2c000
	s_addc_u32 s93, s93, 0
	s_add_u32 s100, s92, 0x2000
	s_addc_u32 s101, s93, 0
	global_load_dwordx4 v[128:131], v205, s[100:101]
	global_load_dwordx4 v[148:151], v205, s[92:93]
	s_waitcnt vmcnt(11)
	v_lshlrev_b32_e32 v212, 16, v152
	v_and_b32_e32 v213, 0xffff0000, v152
	v_lshlrev_b32_e32 v214, 16, v153
	v_and_b32_e32 v215, 0xffff0000, v153
	v_lshlrev_b32_e32 v200, 16, v154
	v_and_b32_e32 v201, 0xffff0000, v154
	v_lshlrev_b32_e32 v202, 16, v155
	v_and_b32_e32 v203, 0xffff0000, v155
	v_mul_f32_e32 v212, 0xbfb8aa3b, v212
	v_mul_f32_e32 v213, 0xbfb8aa3b, v213
	v_mul_f32_e32 v214, 0xbfb8aa3b, v214
	v_mul_f32_e32 v215, 0xbfb8aa3b, v215
	v_mul_f32_e32 v200, 0xbfb8aa3b, v200
	v_mul_f32_e32 v201, 0xbfb8aa3b, v201
	v_mul_f32_e32 v202, 0xbfb8aa3b, v202
	v_mul_f32_e32 v203, 0xbfb8aa3b, v203
	v_exp_f32_e32 v212, v212
	v_exp_f32_e32 v213, v213
	v_exp_f32_e32 v214, v214
	v_exp_f32_e32 v215, v215
	v_exp_f32_e32 v200, v200
	v_exp_f32_e32 v201, v201
	v_exp_f32_e32 v202, v202
	v_exp_f32_e32 v203, v203
	s_nop 0
	v_add_f32_e32 v212, 1.0, v212
	v_add_f32_e32 v213, 1.0, v213
	v_add_f32_e32 v214, 1.0, v214
	v_add_f32_e32 v215, 1.0, v215
	v_add_f32_e32 v200, 1.0, v200
	v_add_f32_e32 v201, 1.0, v201
	v_add_f32_e32 v202, 1.0, v202
	v_add_f32_e32 v203, 1.0, v203
	v_rcp_f32_e32 v212, v212
	v_rcp_f32_e32 v213, v213
	v_rcp_f32_e32 v214, v214
	v_rcp_f32_e32 v215, v215
	v_rcp_f32_e32 v200, v200
	v_rcp_f32_e32 v201, v201
	v_rcp_f32_e32 v202, v202
	v_rcp_f32_e32 v203, v203
	s_nop 0
	v_mul_f32_e32 v116, v116, v212
	v_mul_f32_e32 v117, v117, v213
	v_mul_f32_e32 v118, v118, v214
	v_mul_f32_e32 v119, v119, v215
	v_mul_f32_e32 v112, v112, v200
	v_mul_f32_e32 v113, v113, v201
	v_mul_f32_e32 v114, v114, v202
	v_mul_f32_e32 v115, v115, v203
	v_lshlrev_b32_e32 v212, 16, v164
	v_and_b32_e32 v213, 0xffff0000, v164
	v_lshlrev_b32_e32 v214, 16, v165
	v_and_b32_e32 v215, 0xffff0000, v165
	v_lshlrev_b32_e32 v200, 16, v166
	v_and_b32_e32 v201, 0xffff0000, v166
	v_lshlrev_b32_e32 v202, 16, v167
	v_and_b32_e32 v203, 0xffff0000, v167
	v_add_f32_e32 v116, v116, v212
	v_add_f32_e32 v117, v117, v213
	v_add_f32_e32 v118, v118, v214
	v_add_f32_e32 v119, v119, v215
	v_add_f32_e32 v112, v112, v200
	v_add_f32_e32 v113, v113, v201
	v_add_f32_e32 v114, v114, v202
	v_add_f32_e32 v115, v115, v203
	v_cvt_pk_bf16_f32 v116, v116, v117
	v_cvt_pk_bf16_f32 v117, v118, v119
	v_cvt_pk_bf16_f32 v118, v112, v113
	v_cvt_pk_bf16_f32 v119, v114, v115
	global_store_dwordx4 v205, v[116:119], s[88:89] offset:256
	s_add_u32 s100, s92, 0x2000
	s_addc_u32 s101, s93, 0
	global_load_dwordx4 v[152:155], v205, s[100:101] offset:256
	global_load_dwordx4 v[164:167], v205, s[92:93] offset:256
	s_add_u32 s88, s88, 0x2c000
	s_addc_u32 s89, s89, 0
	s_waitcnt vmcnt(12)
	v_lshlrev_b32_e32 v212, 16, v168
	v_and_b32_e32 v213, 0xffff0000, v168
	v_lshlrev_b32_e32 v214, 16, v169
	v_and_b32_e32 v215, 0xffff0000, v169
	v_lshlrev_b32_e32 v200, 16, v170
	v_and_b32_e32 v201, 0xffff0000, v170
	v_lshlrev_b32_e32 v202, 16, v171
	v_and_b32_e32 v203, 0xffff0000, v171
	v_mul_f32_e32 v212, 0xbfb8aa3b, v212
	v_mul_f32_e32 v213, 0xbfb8aa3b, v213
	v_mul_f32_e32 v214, 0xbfb8aa3b, v214
	v_mul_f32_e32 v215, 0xbfb8aa3b, v215
	v_mul_f32_e32 v200, 0xbfb8aa3b, v200
	v_mul_f32_e32 v201, 0xbfb8aa3b, v201
	v_mul_f32_e32 v202, 0xbfb8aa3b, v202
	v_mul_f32_e32 v203, 0xbfb8aa3b, v203
	v_exp_f32_e32 v212, v212
	v_exp_f32_e32 v213, v213
	v_exp_f32_e32 v214, v214
	v_exp_f32_e32 v215, v215
	v_exp_f32_e32 v200, v200
	v_exp_f32_e32 v201, v201
	v_exp_f32_e32 v202, v202
	v_exp_f32_e32 v203, v203
	s_nop 0
	v_add_f32_e32 v212, 1.0, v212
	v_add_f32_e32 v213, 1.0, v213
	v_add_f32_e32 v214, 1.0, v214
	v_add_f32_e32 v215, 1.0, v215
	v_add_f32_e32 v200, 1.0, v200
	v_add_f32_e32 v201, 1.0, v201
	v_add_f32_e32 v202, 1.0, v202
	v_add_f32_e32 v203, 1.0, v203
	v_rcp_f32_e32 v212, v212
	v_rcp_f32_e32 v213, v213
	v_rcp_f32_e32 v214, v214
	v_rcp_f32_e32 v215, v215
	v_rcp_f32_e32 v200, v200
	v_rcp_f32_e32 v201, v201
	v_rcp_f32_e32 v202, v202
	v_rcp_f32_e32 v203, v203
	s_nop 0
	v_mul_f32_e32 v108, v108, v212
	v_mul_f32_e32 v109, v109, v213
	v_mul_f32_e32 v110, v110, v214
	v_mul_f32_e32 v111, v111, v215
	v_mul_f32_e32 v104, v104, v200
	v_mul_f32_e32 v105, v105, v201
	v_mul_f32_e32 v106, v106, v202
	v_mul_f32_e32 v107, v107, v203
	v_lshlrev_b32_e32 v212, 16, v172
	v_and_b32_e32 v213, 0xffff0000, v172
	v_lshlrev_b32_e32 v214, 16, v173
	v_and_b32_e32 v215, 0xffff0000, v173
	v_lshlrev_b32_e32 v200, 16, v174
	v_and_b32_e32 v201, 0xffff0000, v174
	v_lshlrev_b32_e32 v202, 16, v175
	v_and_b32_e32 v203, 0xffff0000, v175
	v_add_f32_e32 v108, v108, v212
	v_add_f32_e32 v109, v109, v213
	v_add_f32_e32 v110, v110, v214
	v_add_f32_e32 v111, v111, v215
	v_add_f32_e32 v104, v104, v200
	v_add_f32_e32 v105, v105, v201
	v_add_f32_e32 v106, v106, v202
	v_add_f32_e32 v107, v107, v203
	v_cvt_pk_bf16_f32 v108, v108, v109
	v_cvt_pk_bf16_f32 v109, v110, v111
	v_cvt_pk_bf16_f32 v110, v104, v105
	v_cvt_pk_bf16_f32 v111, v106, v107
	global_store_dwordx4 v205, v[108:111], s[88:89]
	s_add_u32 s92, s92, 0xdc000
	s_addc_u32 s93, s93, 0
	s_add_u32 s100, s92, 0x2000
	s_addc_u32 s101, s93, 0
	global_load_dwordx4 v[168:171], v205, s[100:101]
	global_load_dwordx4 v[172:175], v205, s[92:93]
	s_waitcnt vmcnt(13)
	v_lshlrev_b32_e32 v212, 16, v176
	v_and_b32_e32 v213, 0xffff0000, v176
	v_lshlrev_b32_e32 v214, 16, v177
	v_and_b32_e32 v215, 0xffff0000, v177
	v_lshlrev_b32_e32 v200, 16, v178
	v_and_b32_e32 v201, 0xffff0000, v178
	v_lshlrev_b32_e32 v202, 16, v179
	v_and_b32_e32 v203, 0xffff0000, v179
	v_mul_f32_e32 v212, 0xbfb8aa3b, v212
	v_mul_f32_e32 v213, 0xbfb8aa3b, v213
	v_mul_f32_e32 v214, 0xbfb8aa3b, v214
	v_mul_f32_e32 v215, 0xbfb8aa3b, v215
	v_mul_f32_e32 v200, 0xbfb8aa3b, v200
	v_mul_f32_e32 v201, 0xbfb8aa3b, v201
	v_mul_f32_e32 v202, 0xbfb8aa3b, v202
	v_mul_f32_e32 v203, 0xbfb8aa3b, v203
	v_exp_f32_e32 v212, v212
	v_exp_f32_e32 v213, v213
	v_exp_f32_e32 v214, v214
	v_exp_f32_e32 v215, v215
	v_exp_f32_e32 v200, v200
	v_exp_f32_e32 v201, v201
	v_exp_f32_e32 v202, v202
	v_exp_f32_e32 v203, v203
	s_nop 0
	v_add_f32_e32 v212, 1.0, v212
	v_add_f32_e32 v213, 1.0, v213
	v_add_f32_e32 v214, 1.0, v214
	v_add_f32_e32 v215, 1.0, v215
	v_add_f32_e32 v200, 1.0, v200
	v_add_f32_e32 v201, 1.0, v201
	v_add_f32_e32 v202, 1.0, v202
	v_add_f32_e32 v203, 1.0, v203
	v_rcp_f32_e32 v212, v212
	v_rcp_f32_e32 v213, v213
	v_rcp_f32_e32 v214, v214
	v_rcp_f32_e32 v215, v215
	v_rcp_f32_e32 v200, v200
	v_rcp_f32_e32 v201, v201
	v_rcp_f32_e32 v202, v202
	v_rcp_f32_e32 v203, v203
	s_nop 0
	v_mul_f32_e32 v100, v100, v212
	v_mul_f32_e32 v101, v101, v213
	v_mul_f32_e32 v102, v102, v214
	v_mul_f32_e32 v103, v103, v215
	v_mul_f32_e32 v96, v96, v200
	v_mul_f32_e32 v97, v97, v201
	v_mul_f32_e32 v98, v98, v202
	v_mul_f32_e32 v99, v99, v203
	v_lshlrev_b32_e32 v212, 16, v180
	v_and_b32_e32 v213, 0xffff0000, v180
	v_lshlrev_b32_e32 v214, 16, v181
	v_and_b32_e32 v215, 0xffff0000, v181
	v_lshlrev_b32_e32 v200, 16, v182
	v_and_b32_e32 v201, 0xffff0000, v182
	v_lshlrev_b32_e32 v202, 16, v183
	v_and_b32_e32 v203, 0xffff0000, v183
	v_add_f32_e32 v100, v100, v212
	v_add_f32_e32 v101, v101, v213
	v_add_f32_e32 v102, v102, v214
	v_add_f32_e32 v103, v103, v215
	v_add_f32_e32 v96, v96, v200
	v_add_f32_e32 v97, v97, v201
	v_add_f32_e32 v98, v98, v202
	v_add_f32_e32 v99, v99, v203
	v_cvt_pk_bf16_f32 v100, v100, v101
	v_cvt_pk_bf16_f32 v101, v102, v103
	v_cvt_pk_bf16_f32 v102, v96, v97
	v_cvt_pk_bf16_f32 v103, v98, v99
	global_store_dwordx4 v205, v[100:103], s[88:89] offset:256
	s_add_u32 s100, s92, 0x2000
	s_addc_u32 s101, s93, 0
	global_load_dwordx4 v[176:179], v205, s[100:101] offset:256
	global_load_dwordx4 v[180:183], v205, s[92:93] offset:256
	s_add_u32 s88, s88, 0x2c000
	s_addc_u32 s89, s89, 0
	s_waitcnt vmcnt(14)
	v_lshlrev_b32_e32 v212, 16, v184
	v_and_b32_e32 v213, 0xffff0000, v184
	v_lshlrev_b32_e32 v214, 16, v185
	v_and_b32_e32 v215, 0xffff0000, v185
	v_lshlrev_b32_e32 v200, 16, v186
	v_and_b32_e32 v201, 0xffff0000, v186
	v_lshlrev_b32_e32 v202, 16, v187
	v_and_b32_e32 v203, 0xffff0000, v187
	v_mul_f32_e32 v212, 0xbfb8aa3b, v212
	v_mul_f32_e32 v213, 0xbfb8aa3b, v213
	v_mul_f32_e32 v214, 0xbfb8aa3b, v214
	v_mul_f32_e32 v215, 0xbfb8aa3b, v215
	v_mul_f32_e32 v200, 0xbfb8aa3b, v200
	v_mul_f32_e32 v201, 0xbfb8aa3b, v201
	v_mul_f32_e32 v202, 0xbfb8aa3b, v202
	v_mul_f32_e32 v203, 0xbfb8aa3b, v203
	v_exp_f32_e32 v212, v212
	v_exp_f32_e32 v213, v213
	v_exp_f32_e32 v214, v214
	v_exp_f32_e32 v215, v215
	v_exp_f32_e32 v200, v200
	v_exp_f32_e32 v201, v201
	v_exp_f32_e32 v202, v202
	v_exp_f32_e32 v203, v203
	s_nop 0
	v_add_f32_e32 v212, 1.0, v212
	v_add_f32_e32 v213, 1.0, v213
	v_add_f32_e32 v214, 1.0, v214
	v_add_f32_e32 v215, 1.0, v215
	v_add_f32_e32 v200, 1.0, v200
	v_add_f32_e32 v201, 1.0, v201
	v_add_f32_e32 v202, 1.0, v202
	v_add_f32_e32 v203, 1.0, v203
	v_rcp_f32_e32 v212, v212
	v_rcp_f32_e32 v213, v213
	v_rcp_f32_e32 v214, v214
	v_rcp_f32_e32 v215, v215
	v_rcp_f32_e32 v200, v200
	v_rcp_f32_e32 v201, v201
	v_rcp_f32_e32 v202, v202
	v_rcp_f32_e32 v203, v203
	s_nop 0
	v_mul_f32_e32 v92, v92, v212
	v_mul_f32_e32 v93, v93, v213
	v_mul_f32_e32 v94, v94, v214
	v_mul_f32_e32 v95, v95, v215
	v_mul_f32_e32 v88, v88, v200
	v_mul_f32_e32 v89, v89, v201
	v_mul_f32_e32 v90, v90, v202
	v_mul_f32_e32 v91, v91, v203
	v_lshlrev_b32_e32 v212, 16, v188
	v_and_b32_e32 v213, 0xffff0000, v188
	v_lshlrev_b32_e32 v214, 16, v189
	v_and_b32_e32 v215, 0xffff0000, v189
	v_lshlrev_b32_e32 v200, 16, v190
	v_and_b32_e32 v201, 0xffff0000, v190
	v_lshlrev_b32_e32 v202, 16, v191
	v_and_b32_e32 v203, 0xffff0000, v191
	v_add_f32_e32 v92, v92, v212
	v_add_f32_e32 v93, v93, v213
	v_add_f32_e32 v94, v94, v214
	v_add_f32_e32 v95, v95, v215
	v_add_f32_e32 v88, v88, v200
	v_add_f32_e32 v89, v89, v201
	v_add_f32_e32 v90, v90, v202
	v_add_f32_e32 v91, v91, v203
	v_cvt_pk_bf16_f32 v92, v92, v93
	v_cvt_pk_bf16_f32 v93, v94, v95
	v_cvt_pk_bf16_f32 v94, v88, v89
	v_cvt_pk_bf16_f32 v95, v90, v91
	global_store_dwordx4 v205, v[92:95], s[88:89]
	s_add_u32 s92, s92, 0x2c000
	s_addc_u32 s93, s93, 0
	s_add_u32 s100, s92, 0x2000
	s_addc_u32 s101, s93, 0
	global_load_dwordx4 v[184:187], v205, s[100:101]
	global_load_dwordx4 v[188:191], v205, s[92:93]
	s_waitcnt vmcnt(15)
	v_lshlrev_b32_e32 v212, 16, v192
	v_and_b32_e32 v213, 0xffff0000, v192
	v_lshlrev_b32_e32 v214, 16, v193
	v_and_b32_e32 v215, 0xffff0000, v193
	v_lshlrev_b32_e32 v200, 16, v194
	v_and_b32_e32 v201, 0xffff0000, v194
	v_lshlrev_b32_e32 v202, 16, v195
	v_and_b32_e32 v203, 0xffff0000, v195
	v_mul_f32_e32 v212, 0xbfb8aa3b, v212
	v_mul_f32_e32 v213, 0xbfb8aa3b, v213
	v_mul_f32_e32 v214, 0xbfb8aa3b, v214
	v_mul_f32_e32 v215, 0xbfb8aa3b, v215
	v_mul_f32_e32 v200, 0xbfb8aa3b, v200
	v_mul_f32_e32 v201, 0xbfb8aa3b, v201
	v_mul_f32_e32 v202, 0xbfb8aa3b, v202
	v_mul_f32_e32 v203, 0xbfb8aa3b, v203
	v_exp_f32_e32 v212, v212
	v_exp_f32_e32 v213, v213
	v_exp_f32_e32 v214, v214
	v_exp_f32_e32 v215, v215
	v_exp_f32_e32 v200, v200
	v_exp_f32_e32 v201, v201
	v_exp_f32_e32 v202, v202
	v_exp_f32_e32 v203, v203
	s_nop 0
	v_add_f32_e32 v212, 1.0, v212
	v_add_f32_e32 v213, 1.0, v213
	v_add_f32_e32 v214, 1.0, v214
	v_add_f32_e32 v215, 1.0, v215
	v_add_f32_e32 v200, 1.0, v200
	v_add_f32_e32 v201, 1.0, v201
	v_add_f32_e32 v202, 1.0, v202
	v_add_f32_e32 v203, 1.0, v203
	v_rcp_f32_e32 v212, v212
	v_rcp_f32_e32 v213, v213
	v_rcp_f32_e32 v214, v214
	v_rcp_f32_e32 v215, v215
	v_rcp_f32_e32 v200, v200
	v_rcp_f32_e32 v201, v201
	v_rcp_f32_e32 v202, v202
	v_rcp_f32_e32 v203, v203
	s_nop 0
	v_mul_f32_e32 v84, v84, v212
	v_mul_f32_e32 v85, v85, v213
	v_mul_f32_e32 v86, v86, v214
	v_mul_f32_e32 v87, v87, v215
	v_mul_f32_e32 v80, v80, v200
	v_mul_f32_e32 v81, v81, v201
	v_mul_f32_e32 v82, v82, v202
	v_mul_f32_e32 v83, v83, v203
	v_lshlrev_b32_e32 v212, 16, v196
	v_and_b32_e32 v213, 0xffff0000, v196
	v_lshlrev_b32_e32 v214, 16, v197
	v_and_b32_e32 v215, 0xffff0000, v197
	v_lshlrev_b32_e32 v200, 16, v198
	v_and_b32_e32 v201, 0xffff0000, v198
	v_lshlrev_b32_e32 v202, 16, v199
	v_and_b32_e32 v203, 0xffff0000, v199
	v_add_f32_e32 v84, v84, v212
	v_add_f32_e32 v85, v85, v213
	v_add_f32_e32 v86, v86, v214
	v_add_f32_e32 v87, v87, v215
	v_add_f32_e32 v80, v80, v200
	v_add_f32_e32 v81, v81, v201
	v_add_f32_e32 v82, v82, v202
	v_add_f32_e32 v83, v83, v203
	v_cvt_pk_bf16_f32 v84, v84, v85
	v_cvt_pk_bf16_f32 v85, v86, v87
	v_cvt_pk_bf16_f32 v86, v80, v81
	v_cvt_pk_bf16_f32 v87, v82, v83
	global_store_dwordx4 v205, v[84:87], s[88:89] offset:256
	s_add_u32 s100, s92, 0x2000
	s_addc_u32 s101, s93, 0
	global_load_dwordx4 v[192:195], v205, s[100:101] offset:256
	global_load_dwordx4 v[196:199], v205, s[92:93] offset:256
	s_add_u32 s88, s88, 0x2c000
	s_addc_u32 s89, s89, 0
	s_waitcnt vmcnt(15)
	v_lshlrev_b32_e32 v212, 16, v128
	v_and_b32_e32 v213, 0xffff0000, v128
	v_lshlrev_b32_e32 v214, 16, v129
	v_and_b32_e32 v215, 0xffff0000, v129
	v_lshlrev_b32_e32 v200, 16, v130
	v_and_b32_e32 v201, 0xffff0000, v130
	v_lshlrev_b32_e32 v202, 16, v131
	v_and_b32_e32 v203, 0xffff0000, v131
	v_mul_f32_e32 v212, 0xbfb8aa3b, v212
	v_mul_f32_e32 v213, 0xbfb8aa3b, v213
	v_mul_f32_e32 v214, 0xbfb8aa3b, v214
	v_mul_f32_e32 v215, 0xbfb8aa3b, v215
	v_mul_f32_e32 v200, 0xbfb8aa3b, v200
	v_mul_f32_e32 v201, 0xbfb8aa3b, v201
	v_mul_f32_e32 v202, 0xbfb8aa3b, v202
	v_mul_f32_e32 v203, 0xbfb8aa3b, v203
	v_exp_f32_e32 v212, v212
	v_exp_f32_e32 v213, v213
	v_exp_f32_e32 v214, v214
	v_exp_f32_e32 v215, v215
	v_exp_f32_e32 v200, v200
	v_exp_f32_e32 v201, v201
	v_exp_f32_e32 v202, v202
	v_exp_f32_e32 v203, v203
	s_nop 0
	v_add_f32_e32 v212, 1.0, v212
	v_add_f32_e32 v213, 1.0, v213
	v_add_f32_e32 v214, 1.0, v214
	v_add_f32_e32 v215, 1.0, v215
	v_add_f32_e32 v200, 1.0, v200
	v_add_f32_e32 v201, 1.0, v201
	v_add_f32_e32 v202, 1.0, v202
	v_add_f32_e32 v203, 1.0, v203
	v_rcp_f32_e32 v212, v212
	v_rcp_f32_e32 v213, v213
	v_rcp_f32_e32 v214, v214
	v_rcp_f32_e32 v215, v215
	v_rcp_f32_e32 v200, v200
	v_rcp_f32_e32 v201, v201
	v_rcp_f32_e32 v202, v202
	v_rcp_f32_e32 v203, v203
	s_nop 0
	v_mul_f32_e32 v76, v76, v212
	v_mul_f32_e32 v77, v77, v213
	v_mul_f32_e32 v78, v78, v214
	v_mul_f32_e32 v79, v79, v215
	v_mul_f32_e32 v72, v72, v200
	v_mul_f32_e32 v73, v73, v201
	v_mul_f32_e32 v74, v74, v202
	v_mul_f32_e32 v75, v75, v203
	v_lshlrev_b32_e32 v212, 16, v148
	v_and_b32_e32 v213, 0xffff0000, v148
	v_lshlrev_b32_e32 v214, 16, v149
	v_and_b32_e32 v215, 0xffff0000, v149
	v_lshlrev_b32_e32 v200, 16, v150
	v_and_b32_e32 v201, 0xffff0000, v150
	v_lshlrev_b32_e32 v202, 16, v151
	v_and_b32_e32 v203, 0xffff0000, v151
	v_add_f32_e32 v76, v76, v212
	v_add_f32_e32 v77, v77, v213
	v_add_f32_e32 v78, v78, v214
	v_add_f32_e32 v79, v79, v215
	v_add_f32_e32 v72, v72, v200
	v_add_f32_e32 v73, v73, v201
	v_add_f32_e32 v74, v74, v202
	v_add_f32_e32 v75, v75, v203
	v_cvt_pk_bf16_f32 v76, v76, v77
	v_cvt_pk_bf16_f32 v77, v78, v79
	v_cvt_pk_bf16_f32 v78, v72, v73
	v_cvt_pk_bf16_f32 v79, v74, v75
	global_store_dwordx4 v205, v[76:79], s[88:89]
	s_add_u32 s92, s92, 0x2c000
	s_addc_u32 s93, s93, 0
	s_add_u32 s100, s92, 0x2000
	s_addc_u32 s101, s93, 0
	global_load_dwordx4 v[128:131], v205, s[100:101]
	global_load_dwordx4 v[148:151], v205, s[92:93]
	s_waitcnt vmcnt(15)
	v_lshlrev_b32_e32 v212, 16, v152
	v_and_b32_e32 v213, 0xffff0000, v152
	v_lshlrev_b32_e32 v214, 16, v153
	v_and_b32_e32 v215, 0xffff0000, v153
	v_lshlrev_b32_e32 v200, 16, v154
	v_and_b32_e32 v201, 0xffff0000, v154
	v_lshlrev_b32_e32 v202, 16, v155
	v_and_b32_e32 v203, 0xffff0000, v155
	v_mul_f32_e32 v212, 0xbfb8aa3b, v212
	v_mul_f32_e32 v213, 0xbfb8aa3b, v213
	v_mul_f32_e32 v214, 0xbfb8aa3b, v214
	v_mul_f32_e32 v215, 0xbfb8aa3b, v215
	v_mul_f32_e32 v200, 0xbfb8aa3b, v200
	v_mul_f32_e32 v201, 0xbfb8aa3b, v201
	v_mul_f32_e32 v202, 0xbfb8aa3b, v202
	v_mul_f32_e32 v203, 0xbfb8aa3b, v203
	v_exp_f32_e32 v212, v212
	v_exp_f32_e32 v213, v213
	v_exp_f32_e32 v214, v214
	v_exp_f32_e32 v215, v215
	v_exp_f32_e32 v200, v200
	v_exp_f32_e32 v201, v201
	v_exp_f32_e32 v202, v202
	v_exp_f32_e32 v203, v203
	s_nop 0
	v_add_f32_e32 v212, 1.0, v212
	v_add_f32_e32 v213, 1.0, v213
	v_add_f32_e32 v214, 1.0, v214
	v_add_f32_e32 v215, 1.0, v215
	v_add_f32_e32 v200, 1.0, v200
	v_add_f32_e32 v201, 1.0, v201
	v_add_f32_e32 v202, 1.0, v202
	v_add_f32_e32 v203, 1.0, v203
	v_rcp_f32_e32 v212, v212
	v_rcp_f32_e32 v213, v213
	v_rcp_f32_e32 v214, v214
	v_rcp_f32_e32 v215, v215
	v_rcp_f32_e32 v200, v200
	v_rcp_f32_e32 v201, v201
	v_rcp_f32_e32 v202, v202
	v_rcp_f32_e32 v203, v203
	s_nop 0
	v_mul_f32_e32 v68, v68, v212
	v_mul_f32_e32 v69, v69, v213
	v_mul_f32_e32 v70, v70, v214
	v_mul_f32_e32 v71, v71, v215
	v_mul_f32_e32 v64, v64, v200
	v_mul_f32_e32 v65, v65, v201
	v_mul_f32_e32 v66, v66, v202
	v_mul_f32_e32 v67, v67, v203
	v_lshlrev_b32_e32 v212, 16, v164
	v_and_b32_e32 v213, 0xffff0000, v164
	v_lshlrev_b32_e32 v214, 16, v165
	v_and_b32_e32 v215, 0xffff0000, v165
	v_lshlrev_b32_e32 v200, 16, v166
	v_and_b32_e32 v201, 0xffff0000, v166
	v_lshlrev_b32_e32 v202, 16, v167
	v_and_b32_e32 v203, 0xffff0000, v167
	v_add_f32_e32 v68, v68, v212
	v_add_f32_e32 v69, v69, v213
	v_add_f32_e32 v70, v70, v214
	v_add_f32_e32 v71, v71, v215
	v_add_f32_e32 v64, v64, v200
	v_add_f32_e32 v65, v65, v201
	v_add_f32_e32 v66, v66, v202
	v_add_f32_e32 v67, v67, v203
	v_cvt_pk_bf16_f32 v68, v68, v69
	v_cvt_pk_bf16_f32 v69, v70, v71
	v_cvt_pk_bf16_f32 v70, v64, v65
	v_cvt_pk_bf16_f32 v71, v66, v67
	global_store_dwordx4 v205, v[68:71], s[88:89] offset:256
	s_add_u32 s100, s92, 0x2000
	s_addc_u32 s101, s93, 0
	global_load_dwordx4 v[152:155], v205, s[100:101] offset:256
	global_load_dwordx4 v[164:167], v205, s[92:93] offset:256
	s_add_u32 s88, s88, 0xdc000
	s_addc_u32 s89, s89, 0
	s_waitcnt vmcnt(15)
	v_lshlrev_b32_e32 v212, 16, v168
	v_and_b32_e32 v213, 0xffff0000, v168
	v_lshlrev_b32_e32 v214, 16, v169
	v_and_b32_e32 v215, 0xffff0000, v169
	v_lshlrev_b32_e32 v200, 16, v170
	v_and_b32_e32 v201, 0xffff0000, v170
	v_lshlrev_b32_e32 v202, 16, v171
	v_and_b32_e32 v203, 0xffff0000, v171
	v_mul_f32_e32 v212, 0xbfb8aa3b, v212
	v_mul_f32_e32 v213, 0xbfb8aa3b, v213
	v_mul_f32_e32 v214, 0xbfb8aa3b, v214
	v_mul_f32_e32 v215, 0xbfb8aa3b, v215
	v_mul_f32_e32 v200, 0xbfb8aa3b, v200
	v_mul_f32_e32 v201, 0xbfb8aa3b, v201
	v_mul_f32_e32 v202, 0xbfb8aa3b, v202
	v_mul_f32_e32 v203, 0xbfb8aa3b, v203
	v_exp_f32_e32 v212, v212
	v_exp_f32_e32 v213, v213
	v_exp_f32_e32 v214, v214
	v_exp_f32_e32 v215, v215
	v_exp_f32_e32 v200, v200
	v_exp_f32_e32 v201, v201
	v_exp_f32_e32 v202, v202
	v_exp_f32_e32 v203, v203
	s_nop 0
	v_add_f32_e32 v212, 1.0, v212
	v_add_f32_e32 v213, 1.0, v213
	v_add_f32_e32 v214, 1.0, v214
	v_add_f32_e32 v215, 1.0, v215
	v_add_f32_e32 v200, 1.0, v200
	v_add_f32_e32 v201, 1.0, v201
	v_add_f32_e32 v202, 1.0, v202
	v_add_f32_e32 v203, 1.0, v203
	v_rcp_f32_e32 v212, v212
	v_rcp_f32_e32 v213, v213
	v_rcp_f32_e32 v214, v214
	v_rcp_f32_e32 v215, v215
	v_rcp_f32_e32 v200, v200
	v_rcp_f32_e32 v201, v201
	v_rcp_f32_e32 v202, v202
	v_rcp_f32_e32 v203, v203
	s_nop 0
	v_mul_f32_e32 v60, v60, v212
	v_mul_f32_e32 v61, v61, v213
	v_mul_f32_e32 v62, v62, v214
	v_mul_f32_e32 v63, v63, v215
	v_mul_f32_e32 v56, v56, v200
	v_mul_f32_e32 v57, v57, v201
	v_mul_f32_e32 v58, v58, v202
	v_mul_f32_e32 v59, v59, v203
	v_lshlrev_b32_e32 v212, 16, v172
	v_and_b32_e32 v213, 0xffff0000, v172
	v_lshlrev_b32_e32 v214, 16, v173
	v_and_b32_e32 v215, 0xffff0000, v173
	v_lshlrev_b32_e32 v200, 16, v174
	v_and_b32_e32 v201, 0xffff0000, v174
	v_lshlrev_b32_e32 v202, 16, v175
	v_and_b32_e32 v203, 0xffff0000, v175
	v_add_f32_e32 v60, v60, v212
	v_add_f32_e32 v61, v61, v213
	v_add_f32_e32 v62, v62, v214
	v_add_f32_e32 v63, v63, v215
	v_add_f32_e32 v56, v56, v200
	v_add_f32_e32 v57, v57, v201
	v_add_f32_e32 v58, v58, v202
	v_add_f32_e32 v59, v59, v203
	v_cvt_pk_bf16_f32 v60, v60, v61
	v_cvt_pk_bf16_f32 v61, v62, v63
	v_cvt_pk_bf16_f32 v62, v56, v57
	v_cvt_pk_bf16_f32 v63, v58, v59
	global_store_dwordx4 v205, v[60:63], s[88:89]
	s_add_u32 s92, s92, 0x2c000
	s_addc_u32 s93, s93, 0
	s_add_u32 s100, s92, 0x2000
	s_addc_u32 s101, s93, 0
	global_load_dwordx4 v[168:171], v205, s[100:101]
	global_load_dwordx4 v[172:175], v205, s[92:93]
	s_waitcnt vmcnt(15)
	v_lshlrev_b32_e32 v212, 16, v176
	v_and_b32_e32 v213, 0xffff0000, v176
	v_lshlrev_b32_e32 v214, 16, v177
	v_and_b32_e32 v215, 0xffff0000, v177
	v_lshlrev_b32_e32 v200, 16, v178
	v_and_b32_e32 v201, 0xffff0000, v178
	v_lshlrev_b32_e32 v202, 16, v179
	v_and_b32_e32 v203, 0xffff0000, v179
	v_mul_f32_e32 v212, 0xbfb8aa3b, v212
	v_mul_f32_e32 v213, 0xbfb8aa3b, v213
	v_mul_f32_e32 v214, 0xbfb8aa3b, v214
	v_mul_f32_e32 v215, 0xbfb8aa3b, v215
	v_mul_f32_e32 v200, 0xbfb8aa3b, v200
	v_mul_f32_e32 v201, 0xbfb8aa3b, v201
	v_mul_f32_e32 v202, 0xbfb8aa3b, v202
	v_mul_f32_e32 v203, 0xbfb8aa3b, v203
	v_exp_f32_e32 v212, v212
	v_exp_f32_e32 v213, v213
	v_exp_f32_e32 v214, v214
	v_exp_f32_e32 v215, v215
	v_exp_f32_e32 v200, v200
	v_exp_f32_e32 v201, v201
	v_exp_f32_e32 v202, v202
	v_exp_f32_e32 v203, v203
	s_nop 0
	v_add_f32_e32 v212, 1.0, v212
	v_add_f32_e32 v213, 1.0, v213
	v_add_f32_e32 v214, 1.0, v214
	v_add_f32_e32 v215, 1.0, v215
	v_add_f32_e32 v200, 1.0, v200
	v_add_f32_e32 v201, 1.0, v201
	v_add_f32_e32 v202, 1.0, v202
	v_add_f32_e32 v203, 1.0, v203
	v_rcp_f32_e32 v212, v212
	v_rcp_f32_e32 v213, v213
	v_rcp_f32_e32 v214, v214
	v_rcp_f32_e32 v215, v215
	v_rcp_f32_e32 v200, v200
	v_rcp_f32_e32 v201, v201
	v_rcp_f32_e32 v202, v202
	v_rcp_f32_e32 v203, v203
	s_nop 0
	v_mul_f32_e32 v52, v52, v212
	v_mul_f32_e32 v53, v53, v213
	v_mul_f32_e32 v54, v54, v214
	v_mul_f32_e32 v55, v55, v215
	v_mul_f32_e32 v48, v48, v200
	v_mul_f32_e32 v49, v49, v201
	v_mul_f32_e32 v50, v50, v202
	v_mul_f32_e32 v51, v51, v203
	v_lshlrev_b32_e32 v212, 16, v180
	v_and_b32_e32 v213, 0xffff0000, v180
	v_lshlrev_b32_e32 v214, 16, v181
	v_and_b32_e32 v215, 0xffff0000, v181
	v_lshlrev_b32_e32 v200, 16, v182
	v_and_b32_e32 v201, 0xffff0000, v182
	v_lshlrev_b32_e32 v202, 16, v183
	v_and_b32_e32 v203, 0xffff0000, v183
	v_add_f32_e32 v52, v52, v212
	v_add_f32_e32 v53, v53, v213
	v_add_f32_e32 v54, v54, v214
	v_add_f32_e32 v55, v55, v215
	v_add_f32_e32 v48, v48, v200
	v_add_f32_e32 v49, v49, v201
	v_add_f32_e32 v50, v50, v202
	v_add_f32_e32 v51, v51, v203
	v_cvt_pk_bf16_f32 v52, v52, v53
	v_cvt_pk_bf16_f32 v53, v54, v55
	v_cvt_pk_bf16_f32 v54, v48, v49
	v_cvt_pk_bf16_f32 v55, v50, v51
	global_store_dwordx4 v205, v[52:55], s[88:89] offset:256
	s_add_u32 s100, s92, 0x2000
	s_addc_u32 s101, s93, 0
	global_load_dwordx4 v[176:179], v205, s[100:101] offset:256
	global_load_dwordx4 v[180:183], v205, s[92:93] offset:256
	s_add_u32 s88, s88, 0x2c000
	s_addc_u32 s89, s89, 0
	s_waitcnt vmcnt(15)
	v_lshlrev_b32_e32 v212, 16, v184
	v_and_b32_e32 v213, 0xffff0000, v184
	v_lshlrev_b32_e32 v214, 16, v185
	v_and_b32_e32 v215, 0xffff0000, v185
	v_lshlrev_b32_e32 v200, 16, v186
	v_and_b32_e32 v201, 0xffff0000, v186
	v_lshlrev_b32_e32 v202, 16, v187
	v_and_b32_e32 v203, 0xffff0000, v187
	v_mul_f32_e32 v212, 0xbfb8aa3b, v212
	v_mul_f32_e32 v213, 0xbfb8aa3b, v213
	v_mul_f32_e32 v214, 0xbfb8aa3b, v214
	v_mul_f32_e32 v215, 0xbfb8aa3b, v215
	v_mul_f32_e32 v200, 0xbfb8aa3b, v200
	v_mul_f32_e32 v201, 0xbfb8aa3b, v201
	v_mul_f32_e32 v202, 0xbfb8aa3b, v202
	v_mul_f32_e32 v203, 0xbfb8aa3b, v203
	v_exp_f32_e32 v212, v212
	v_exp_f32_e32 v213, v213
	v_exp_f32_e32 v214, v214
	v_exp_f32_e32 v215, v215
	v_exp_f32_e32 v200, v200
	v_exp_f32_e32 v201, v201
	v_exp_f32_e32 v202, v202
	v_exp_f32_e32 v203, v203
	s_nop 0
	v_add_f32_e32 v212, 1.0, v212
	v_add_f32_e32 v213, 1.0, v213
	v_add_f32_e32 v214, 1.0, v214
	v_add_f32_e32 v215, 1.0, v215
	v_add_f32_e32 v200, 1.0, v200
	v_add_f32_e32 v201, 1.0, v201
	v_add_f32_e32 v202, 1.0, v202
	v_add_f32_e32 v203, 1.0, v203
	v_rcp_f32_e32 v212, v212
	v_rcp_f32_e32 v213, v213
	v_rcp_f32_e32 v214, v214
	v_rcp_f32_e32 v215, v215
	v_rcp_f32_e32 v200, v200
	v_rcp_f32_e32 v201, v201
	v_rcp_f32_e32 v202, v202
	v_rcp_f32_e32 v203, v203
	s_nop 0
	v_mul_f32_e32 v44, v44, v212
	v_mul_f32_e32 v45, v45, v213
	v_mul_f32_e32 v46, v46, v214
	v_mul_f32_e32 v47, v47, v215
	v_mul_f32_e32 v40, v40, v200
	v_mul_f32_e32 v41, v41, v201
	v_mul_f32_e32 v42, v42, v202
	v_mul_f32_e32 v43, v43, v203
	v_lshlrev_b32_e32 v212, 16, v188
	v_and_b32_e32 v213, 0xffff0000, v188
	v_lshlrev_b32_e32 v214, 16, v189
	v_and_b32_e32 v215, 0xffff0000, v189
	v_lshlrev_b32_e32 v200, 16, v190
	v_and_b32_e32 v201, 0xffff0000, v190
	v_lshlrev_b32_e32 v202, 16, v191
	v_and_b32_e32 v203, 0xffff0000, v191
	v_add_f32_e32 v44, v44, v212
	v_add_f32_e32 v45, v45, v213
	v_add_f32_e32 v46, v46, v214
	v_add_f32_e32 v47, v47, v215
	v_add_f32_e32 v40, v40, v200
	v_add_f32_e32 v41, v41, v201
	v_add_f32_e32 v42, v42, v202
	v_add_f32_e32 v43, v43, v203
	v_cvt_pk_bf16_f32 v44, v44, v45
	v_cvt_pk_bf16_f32 v45, v46, v47
	v_cvt_pk_bf16_f32 v46, v40, v41
	v_cvt_pk_bf16_f32 v47, v42, v43
	global_store_dwordx4 v205, v[44:47], s[88:89]
	s_waitcnt vmcnt(13)
	v_lshlrev_b32_e32 v212, 16, v192
	v_and_b32_e32 v213, 0xffff0000, v192
	v_lshlrev_b32_e32 v214, 16, v193
	v_and_b32_e32 v215, 0xffff0000, v193
	v_lshlrev_b32_e32 v200, 16, v194
	v_and_b32_e32 v201, 0xffff0000, v194
	v_lshlrev_b32_e32 v202, 16, v195
	v_and_b32_e32 v203, 0xffff0000, v195
	v_mul_f32_e32 v212, 0xbfb8aa3b, v212
	v_mul_f32_e32 v213, 0xbfb8aa3b, v213
	v_mul_f32_e32 v214, 0xbfb8aa3b, v214
	v_mul_f32_e32 v215, 0xbfb8aa3b, v215
	v_mul_f32_e32 v200, 0xbfb8aa3b, v200
	v_mul_f32_e32 v201, 0xbfb8aa3b, v201
	v_mul_f32_e32 v202, 0xbfb8aa3b, v202
	v_mul_f32_e32 v203, 0xbfb8aa3b, v203
	v_exp_f32_e32 v212, v212
	v_exp_f32_e32 v213, v213
	v_exp_f32_e32 v214, v214
	v_exp_f32_e32 v215, v215
	v_exp_f32_e32 v200, v200
	v_exp_f32_e32 v201, v201
	v_exp_f32_e32 v202, v202
	v_exp_f32_e32 v203, v203
	s_nop 0
	v_add_f32_e32 v212, 1.0, v212
	v_add_f32_e32 v213, 1.0, v213
	v_add_f32_e32 v214, 1.0, v214
	v_add_f32_e32 v215, 1.0, v215
	v_add_f32_e32 v200, 1.0, v200
	v_add_f32_e32 v201, 1.0, v201
	v_add_f32_e32 v202, 1.0, v202
	v_add_f32_e32 v203, 1.0, v203
	v_rcp_f32_e32 v212, v212
	v_rcp_f32_e32 v213, v213
	v_rcp_f32_e32 v214, v214
	v_rcp_f32_e32 v215, v215
	v_rcp_f32_e32 v200, v200
	v_rcp_f32_e32 v201, v201
	v_rcp_f32_e32 v202, v202
	v_rcp_f32_e32 v203, v203
	s_nop 0
	v_mul_f32_e32 v36, v36, v212
	v_mul_f32_e32 v37, v37, v213
	v_mul_f32_e32 v38, v38, v214
	v_mul_f32_e32 v39, v39, v215
	v_mul_f32_e32 v32, v32, v200
	v_mul_f32_e32 v33, v33, v201
	v_mul_f32_e32 v34, v34, v202
	v_mul_f32_e32 v35, v35, v203
	v_lshlrev_b32_e32 v212, 16, v196
	v_and_b32_e32 v213, 0xffff0000, v196
	v_lshlrev_b32_e32 v214, 16, v197
	v_and_b32_e32 v215, 0xffff0000, v197
	v_lshlrev_b32_e32 v200, 16, v198
	v_and_b32_e32 v201, 0xffff0000, v198
	v_lshlrev_b32_e32 v202, 16, v199
	v_and_b32_e32 v203, 0xffff0000, v199
	v_add_f32_e32 v36, v36, v212
	v_add_f32_e32 v37, v37, v213
	v_add_f32_e32 v38, v38, v214
	v_add_f32_e32 v39, v39, v215
	v_add_f32_e32 v32, v32, v200
	v_add_f32_e32 v33, v33, v201
	v_add_f32_e32 v34, v34, v202
	v_add_f32_e32 v35, v35, v203
	v_cvt_pk_bf16_f32 v36, v36, v37
	v_cvt_pk_bf16_f32 v37, v38, v39
	v_cvt_pk_bf16_f32 v38, v32, v33
	v_cvt_pk_bf16_f32 v39, v34, v35
	global_store_dwordx4 v205, v[36:39], s[88:89] offset:256
	s_add_u32 s88, s88, 0x2c000
	s_addc_u32 s89, s89, 0
	s_waitcnt vmcnt(11)
	v_lshlrev_b32_e32 v212, 16, v128
	v_and_b32_e32 v213, 0xffff0000, v128
	v_lshlrev_b32_e32 v214, 16, v129
	v_and_b32_e32 v215, 0xffff0000, v129
	v_lshlrev_b32_e32 v200, 16, v130
	v_and_b32_e32 v201, 0xffff0000, v130
	v_lshlrev_b32_e32 v202, 16, v131
	v_and_b32_e32 v203, 0xffff0000, v131
	v_mul_f32_e32 v212, 0xbfb8aa3b, v212
	v_mul_f32_e32 v213, 0xbfb8aa3b, v213
	v_mul_f32_e32 v214, 0xbfb8aa3b, v214
	v_mul_f32_e32 v215, 0xbfb8aa3b, v215
	v_mul_f32_e32 v200, 0xbfb8aa3b, v200
	v_mul_f32_e32 v201, 0xbfb8aa3b, v201
	v_mul_f32_e32 v202, 0xbfb8aa3b, v202
	v_mul_f32_e32 v203, 0xbfb8aa3b, v203
	v_exp_f32_e32 v212, v212
	v_exp_f32_e32 v213, v213
	v_exp_f32_e32 v214, v214
	v_exp_f32_e32 v215, v215
	v_exp_f32_e32 v200, v200
	v_exp_f32_e32 v201, v201
	v_exp_f32_e32 v202, v202
	v_exp_f32_e32 v203, v203
	s_nop 0
	v_add_f32_e32 v212, 1.0, v212
	v_add_f32_e32 v213, 1.0, v213
	v_add_f32_e32 v214, 1.0, v214
	v_add_f32_e32 v215, 1.0, v215
	v_add_f32_e32 v200, 1.0, v200
	v_add_f32_e32 v201, 1.0, v201
	v_add_f32_e32 v202, 1.0, v202
	v_add_f32_e32 v203, 1.0, v203
	v_rcp_f32_e32 v212, v212
	v_rcp_f32_e32 v213, v213
	v_rcp_f32_e32 v214, v214
	v_rcp_f32_e32 v215, v215
	v_rcp_f32_e32 v200, v200
	v_rcp_f32_e32 v201, v201
	v_rcp_f32_e32 v202, v202
	v_rcp_f32_e32 v203, v203
	s_nop 0
	v_mul_f32_e32 v28, v28, v212
	v_mul_f32_e32 v29, v29, v213
	v_mul_f32_e32 v30, v30, v214
	v_mul_f32_e32 v31, v31, v215
	v_mul_f32_e32 v24, v24, v200
	v_mul_f32_e32 v25, v25, v201
	v_mul_f32_e32 v26, v26, v202
	v_mul_f32_e32 v27, v27, v203
	v_lshlrev_b32_e32 v212, 16, v148
	v_and_b32_e32 v213, 0xffff0000, v148
	v_lshlrev_b32_e32 v214, 16, v149
	v_and_b32_e32 v215, 0xffff0000, v149
	v_lshlrev_b32_e32 v200, 16, v150
	v_and_b32_e32 v201, 0xffff0000, v150
	v_lshlrev_b32_e32 v202, 16, v151
	v_and_b32_e32 v203, 0xffff0000, v151
	v_add_f32_e32 v28, v28, v212
	v_add_f32_e32 v29, v29, v213
	v_add_f32_e32 v30, v30, v214
	v_add_f32_e32 v31, v31, v215
	v_add_f32_e32 v24, v24, v200
	v_add_f32_e32 v25, v25, v201
	v_add_f32_e32 v26, v26, v202
	v_add_f32_e32 v27, v27, v203
	v_cvt_pk_bf16_f32 v28, v28, v29
	v_cvt_pk_bf16_f32 v29, v30, v31
	v_cvt_pk_bf16_f32 v30, v24, v25
	v_cvt_pk_bf16_f32 v31, v26, v27
	global_store_dwordx4 v205, v[28:31], s[88:89]
	s_waitcnt vmcnt(9)
	v_lshlrev_b32_e32 v212, 16, v152
	v_and_b32_e32 v213, 0xffff0000, v152
	v_lshlrev_b32_e32 v214, 16, v153
	v_and_b32_e32 v215, 0xffff0000, v153
	v_lshlrev_b32_e32 v200, 16, v154
	v_and_b32_e32 v201, 0xffff0000, v154
	v_lshlrev_b32_e32 v202, 16, v155
	v_and_b32_e32 v203, 0xffff0000, v155
	v_mul_f32_e32 v212, 0xbfb8aa3b, v212
	v_mul_f32_e32 v213, 0xbfb8aa3b, v213
	v_mul_f32_e32 v214, 0xbfb8aa3b, v214
	v_mul_f32_e32 v215, 0xbfb8aa3b, v215
	v_mul_f32_e32 v200, 0xbfb8aa3b, v200
	v_mul_f32_e32 v201, 0xbfb8aa3b, v201
	v_mul_f32_e32 v202, 0xbfb8aa3b, v202
	v_mul_f32_e32 v203, 0xbfb8aa3b, v203
	v_exp_f32_e32 v212, v212
	v_exp_f32_e32 v213, v213
	v_exp_f32_e32 v214, v214
	v_exp_f32_e32 v215, v215
	v_exp_f32_e32 v200, v200
	v_exp_f32_e32 v201, v201
	v_exp_f32_e32 v202, v202
	v_exp_f32_e32 v203, v203
	s_nop 0
	v_add_f32_e32 v212, 1.0, v212
	v_add_f32_e32 v213, 1.0, v213
	v_add_f32_e32 v214, 1.0, v214
	v_add_f32_e32 v215, 1.0, v215
	v_add_f32_e32 v200, 1.0, v200
	v_add_f32_e32 v201, 1.0, v201
	v_add_f32_e32 v202, 1.0, v202
	v_add_f32_e32 v203, 1.0, v203
	v_rcp_f32_e32 v212, v212
	v_rcp_f32_e32 v213, v213
	v_rcp_f32_e32 v214, v214
	v_rcp_f32_e32 v215, v215
	v_rcp_f32_e32 v200, v200
	v_rcp_f32_e32 v201, v201
	v_rcp_f32_e32 v202, v202
	v_rcp_f32_e32 v203, v203
	s_nop 0
	v_mul_f32_e32 v20, v20, v212
	v_mul_f32_e32 v21, v21, v213
	v_mul_f32_e32 v22, v22, v214
	v_mul_f32_e32 v23, v23, v215
	v_mul_f32_e32 v16, v16, v200
	v_mul_f32_e32 v17, v17, v201
	v_mul_f32_e32 v18, v18, v202
	v_mul_f32_e32 v19, v19, v203
	v_lshlrev_b32_e32 v212, 16, v164
	v_and_b32_e32 v213, 0xffff0000, v164
	v_lshlrev_b32_e32 v214, 16, v165
	v_and_b32_e32 v215, 0xffff0000, v165
	v_lshlrev_b32_e32 v200, 16, v166
	v_and_b32_e32 v201, 0xffff0000, v166
	v_lshlrev_b32_e32 v202, 16, v167
	v_and_b32_e32 v203, 0xffff0000, v167
	v_add_f32_e32 v20, v20, v212
	v_add_f32_e32 v21, v21, v213
	v_add_f32_e32 v22, v22, v214
	v_add_f32_e32 v23, v23, v215
	v_add_f32_e32 v16, v16, v200
	v_add_f32_e32 v17, v17, v201
	v_add_f32_e32 v18, v18, v202
	v_add_f32_e32 v19, v19, v203
	v_cvt_pk_bf16_f32 v20, v20, v21
	v_cvt_pk_bf16_f32 v21, v22, v23
	v_cvt_pk_bf16_f32 v22, v16, v17
	v_cvt_pk_bf16_f32 v23, v18, v19
	global_store_dwordx4 v205, v[20:23], s[88:89] offset:256
	s_add_u32 s88, s88, 0x2c000
	s_addc_u32 s89, s89, 0
	s_waitcnt vmcnt(7)
	v_lshlrev_b32_e32 v212, 16, v168
	v_and_b32_e32 v213, 0xffff0000, v168
	v_lshlrev_b32_e32 v214, 16, v169
	v_and_b32_e32 v215, 0xffff0000, v169
	v_lshlrev_b32_e32 v200, 16, v170
	v_and_b32_e32 v201, 0xffff0000, v170
	v_lshlrev_b32_e32 v202, 16, v171
	v_and_b32_e32 v203, 0xffff0000, v171
	v_mul_f32_e32 v212, 0xbfb8aa3b, v212
	v_mul_f32_e32 v213, 0xbfb8aa3b, v213
	v_mul_f32_e32 v214, 0xbfb8aa3b, v214
	v_mul_f32_e32 v215, 0xbfb8aa3b, v215
	v_mul_f32_e32 v200, 0xbfb8aa3b, v200
	v_mul_f32_e32 v201, 0xbfb8aa3b, v201
	v_mul_f32_e32 v202, 0xbfb8aa3b, v202
	v_mul_f32_e32 v203, 0xbfb8aa3b, v203
	v_exp_f32_e32 v212, v212
	v_exp_f32_e32 v213, v213
	v_exp_f32_e32 v214, v214
	v_exp_f32_e32 v215, v215
	v_exp_f32_e32 v200, v200
	v_exp_f32_e32 v201, v201
	v_exp_f32_e32 v202, v202
	v_exp_f32_e32 v203, v203
	s_nop 0
	v_add_f32_e32 v212, 1.0, v212
	v_add_f32_e32 v213, 1.0, v213
	v_add_f32_e32 v214, 1.0, v214
	v_add_f32_e32 v215, 1.0, v215
	v_add_f32_e32 v200, 1.0, v200
	v_add_f32_e32 v201, 1.0, v201
	v_add_f32_e32 v202, 1.0, v202
	v_add_f32_e32 v203, 1.0, v203
	v_rcp_f32_e32 v212, v212
	v_rcp_f32_e32 v213, v213
	v_rcp_f32_e32 v214, v214
	v_rcp_f32_e32 v215, v215
	v_rcp_f32_e32 v200, v200
	v_rcp_f32_e32 v201, v201
	v_rcp_f32_e32 v202, v202
	v_rcp_f32_e32 v203, v203
	s_nop 0
	v_mul_f32_e32 v12, v12, v212
	v_mul_f32_e32 v13, v13, v213
	v_mul_f32_e32 v14, v14, v214
	v_mul_f32_e32 v15, v15, v215
	v_mul_f32_e32 v8, v8, v200
	v_mul_f32_e32 v9, v9, v201
	v_mul_f32_e32 v10, v10, v202
	v_mul_f32_e32 v11, v11, v203
	v_lshlrev_b32_e32 v212, 16, v172
	v_and_b32_e32 v213, 0xffff0000, v172
	v_lshlrev_b32_e32 v214, 16, v173
	v_and_b32_e32 v215, 0xffff0000, v173
	v_lshlrev_b32_e32 v200, 16, v174
	v_and_b32_e32 v201, 0xffff0000, v174
	v_lshlrev_b32_e32 v202, 16, v175
	v_and_b32_e32 v203, 0xffff0000, v175
	v_add_f32_e32 v12, v12, v212
	v_add_f32_e32 v13, v13, v213
	v_add_f32_e32 v14, v14, v214
	v_add_f32_e32 v15, v15, v215
	v_add_f32_e32 v8, v8, v200
	v_add_f32_e32 v9, v9, v201
	v_add_f32_e32 v10, v10, v202
	v_add_f32_e32 v11, v11, v203
	v_cvt_pk_bf16_f32 v12, v12, v13
	v_cvt_pk_bf16_f32 v13, v14, v15
	v_cvt_pk_bf16_f32 v14, v8, v9
	v_cvt_pk_bf16_f32 v15, v10, v11
	global_store_dwordx4 v205, v[12:15], s[88:89]
	s_waitcnt vmcnt(5)
	v_lshlrev_b32_e32 v212, 16, v176
	v_and_b32_e32 v213, 0xffff0000, v176
	v_lshlrev_b32_e32 v214, 16, v177
	v_and_b32_e32 v215, 0xffff0000, v177
	v_lshlrev_b32_e32 v200, 16, v178
	v_and_b32_e32 v201, 0xffff0000, v178
	v_lshlrev_b32_e32 v202, 16, v179
	v_and_b32_e32 v203, 0xffff0000, v179
	v_mul_f32_e32 v212, 0xbfb8aa3b, v212
	v_mul_f32_e32 v213, 0xbfb8aa3b, v213
	v_mul_f32_e32 v214, 0xbfb8aa3b, v214
	v_mul_f32_e32 v215, 0xbfb8aa3b, v215
	v_mul_f32_e32 v200, 0xbfb8aa3b, v200
	v_mul_f32_e32 v201, 0xbfb8aa3b, v201
	v_mul_f32_e32 v202, 0xbfb8aa3b, v202
	v_mul_f32_e32 v203, 0xbfb8aa3b, v203
	v_exp_f32_e32 v212, v212
	v_exp_f32_e32 v213, v213
	v_exp_f32_e32 v214, v214
	v_exp_f32_e32 v215, v215
	v_exp_f32_e32 v200, v200
	v_exp_f32_e32 v201, v201
	v_exp_f32_e32 v202, v202
	v_exp_f32_e32 v203, v203
	s_nop 0
	v_add_f32_e32 v212, 1.0, v212
	v_add_f32_e32 v213, 1.0, v213
	v_add_f32_e32 v214, 1.0, v214
	v_add_f32_e32 v215, 1.0, v215
	v_add_f32_e32 v200, 1.0, v200
	v_add_f32_e32 v201, 1.0, v201
	v_add_f32_e32 v202, 1.0, v202
	v_add_f32_e32 v203, 1.0, v203
	v_rcp_f32_e32 v212, v212
	v_rcp_f32_e32 v213, v213
	v_rcp_f32_e32 v214, v214
	v_rcp_f32_e32 v215, v215
	v_rcp_f32_e32 v200, v200
	v_rcp_f32_e32 v201, v201
	v_rcp_f32_e32 v202, v202
	v_rcp_f32_e32 v203, v203
	s_nop 0
	v_mul_f32_e32 v4, v4, v212
	v_mul_f32_e32 v5, v5, v213
	v_mul_f32_e32 v6, v6, v214
	v_mul_f32_e32 v7, v7, v215
	v_mul_f32_e32 v0, v0, v200
	v_mul_f32_e32 v1, v1, v201
	v_mul_f32_e32 v2, v2, v202
	v_mul_f32_e32 v3, v3, v203
	v_lshlrev_b32_e32 v212, 16, v180
	v_and_b32_e32 v213, 0xffff0000, v180
	v_lshlrev_b32_e32 v214, 16, v181
	v_and_b32_e32 v215, 0xffff0000, v181
	v_lshlrev_b32_e32 v200, 16, v182
	v_and_b32_e32 v201, 0xffff0000, v182
	v_lshlrev_b32_e32 v202, 16, v183
	v_and_b32_e32 v203, 0xffff0000, v183
	v_add_f32_e32 v4, v4, v212
	v_add_f32_e32 v5, v5, v213
	v_add_f32_e32 v6, v6, v214
	v_add_f32_e32 v7, v7, v215
	v_add_f32_e32 v0, v0, v200
	v_add_f32_e32 v1, v1, v201
	v_add_f32_e32 v2, v2, v202
	v_add_f32_e32 v3, v3, v203
	v_cvt_pk_bf16_f32 v4, v4, v5
	v_cvt_pk_bf16_f32 v5, v6, v7
	v_cvt_pk_bf16_f32 v6, v0, v1
	v_cvt_pk_bf16_f32 v7, v2, v3
	global_store_dwordx4 v205, v[4:7], s[88:89] offset:256
	s_and_b64 vcc, exec, s[10:11]
	s_mov_b64 s[10:11], -1
	s_cbranch_vccnz .LBB0_917
	s_andn2_b64 vcc, exec, s[14:15]
	s_cbranch_vccnz .LBB0_916
	s_barrier
	s_branch .LBB0_916
